# w_in tail 64x64 sub-tile K loop rewritten as 4-stage LDS ring (3 K-slices of DMA in flight)
# baseline (speedup 1.0000x reference)
.LBB0_273:
	s_mov_b32 s40, s29
	s_add_i32 s29, s29, s50
	s_cmpk_lt_i32 s29, 0x641
	s_cselect_b64 s[0:1], -1, 0
	s_and_b64 vcc, exec, s[0:1]
	s_cbranch_vccnz .LBB0_384
	s_lshl_b32 s0, s40, 2
	s_sub_i32 s33, 0x1900, s0
	s_cmp_le_i32 s33, s50
	s_mov_b64 s[0:1], -1
	s_cbranch_scc0 .LBB0_384
	s_cmp_ge_i32 s60, s33
	s_cselect_b64 s[0:1], -1, 0
	s_and_b64 vcc, exec, s[0:1]
	s_cbranch_vccnz .LBB0_378
	v_readlane_b32 s2, v241, 15
	s_add_i32 s2, s40, s2
	s_ashr_i32 s3, s2, 5
	s_mul_hi_i32 s4, s3, 0x66666667
	s_lshr_b32 s5, s4, 31
	s_ashr_i32 s4, s4, 1
	s_add_i32 s5, s4, s5
	s_mul_i32 s4, s5, 5
	s_sub_i32 s4, s3, s4
	s_lshl_b32 s3, s5, 10
	s_lshl_b32 s5, s2, 5
	s_lshl_b32 s2, s2, 7
	s_and_b32 s5, s5, 0x380
	s_lshl_b32 s8, s4, 9
	s_and_b32 s2, s2, 0x180
	v_mov_b32_e32 v12, v137
	s_or_b32 s41, s8, s2
	s_or_b32 s2, s45, s5
	v_ashrrev_i32_e32 v2, 6, v12
	v_lshlrev_b32_e32 v13, 4, v2
	s_or_b32 s2, s2, s3
	v_bfe_u32 v3, v12, 3, 3
	v_add_u32_e32 v48, s2, v13
	v_or_b32_e32 v0, v48, v3
	v_ashrrev_i32_e32 v1, 31, v0
	s_or_b32 s8, s41, s94
	v_lshlrev_b64 v[0:1], 11, v[0:1]
	v_lshl_add_u64 v[4:5], s[42:43], 0, v[0:1]
	v_add_u32_e32 v0, s8, v13
	v_or_b32_e32 v0, v0, v3
	v_ashrrev_i32_e32 v1, 31, v0
	v_readlane_b32 s36, v242, 1
	v_and_b32_e32 v8, 63, v12
	v_lshlrev_b64 v[0:1], 11, v[0:1]
	v_readlane_b32 s38, v242, 3
	v_readlane_b32 s39, v242, 4
	v_bfe_u32 v51, v12, 4, 2
	v_and_b32_e32 v10, 7, v12
	v_lshl_add_u64 v[6:7], s[38:39], 0, v[0:1]
	v_lshlrev_b32_e32 v0, 11, v2
	v_lshlrev_b32_e32 v1, 4, v8
	v_add3_u32 v14, 0, v0, v1
	v_bitop3_b32 v0, v51, v12, 7 bitop3:0x78
	v_add_u32_e32 v11, 0x2000, v14
	v_lshlrev_b32_e32 v94, 4, v0
	v_readfirstlane_b32 s35, v14
	v_bitop3_b32 v10, v51, v10, 4 bitop3:0x36
	v_readlane_b32 s37, v242, 2
	v_lshl_add_u64 v[0:1], v[4:5], 0, v[94:95]
	s_mov_b32 m0, s35
	v_lshl_add_u64 v[2:3], v[6:7], 0, v[94:95]
	v_readfirstlane_b32 s36, v11
	v_lshlrev_b32_e32 v94, 4, v10
	v_add_u32_e32 v15, 0x400, v14
	v_lshl_add_u64 v[4:5], v[4:5], 0, v[94:95]
	v_readfirstlane_b32 s37, v15
	v_add_u32_e32 v15, 0x2400, v14
	v_lshl_add_u64 v[6:7], v[6:7], 0, v[94:95]
	v_readfirstlane_b32 s38, v15
	v_add_u32_e32 v15, 0x4000, v14
	v_add_u32_e32 v16, 0x6000, v14
	v_readfirstlane_b32 s2, v15
	v_readfirstlane_b32 s3, v16
	v_add_u32_e32 v15, 0x4400, v14
	v_readfirstlane_b32 s5, v15
	v_add_u32_e32 v14, 0x6400, v14
	v_and_b32_e32 v50, 15, v12
	v_lshrrev_b32_e32 v9, 1, v12
	v_readfirstlane_b32 s34, v14
	v_or_b32_e32 v13, v13, v50
	v_bitop3_b32 v9, v51, v9, 7 bitop3:0x78
	v_lshl_add_u32 v11, v13, 7, 0
	v_lshlrev_b32_e32 v9, 4, v9
	v_add_u32_e32 v10, v11, v9
	v_bfe_u32 v12, v12, 1, 3
	v_lshl_add_u32 v13, v50, 7, 0
	v_bitop3_b32 v12, v51, v12, 4 bitop3:0x36
	v_add_u32_e32 v9, v13, v9
	v_lshlrev_b32_e32 v38, 4, v12
	v_add_u32_e32 v12, v11, v38
	v_add_u32_e32 v11, v13, v38
	s_ashr_i32 s44, s8, 6
	s_cmp_lt_i32 s44, 36
	s_mov_b64 s[2:3], -1
	v_lshrrev_b32_e32 v218, 6, v137
	v_and_b32_e32 v219, 15, v137
	v_bfe_u32 v220, v137, 4, 2
	v_bfe_u32 v221, v137, 1, 3
	v_xor_b32_e32 v220, v220, v221
	v_lshlrev_b32_e32 v220, 4, v220
	v_lshl_add_u32 v221, v218, 4, v219
	v_lshlrev_b32_e32 v222, 11, v218
	v_lshl_add_u32 v218, v221, 7, v220
	v_lshl_add_u32 v219, v219, 7, v220
	v_add_u32_e32 v219, 0x2000, v219
	v_xor_b32_e32 v220, 64, v218
	v_xor_b32_e32 v221, 64, v219
	v_readfirstlane_b32 s36, v222
	s_mov_b64 s[38:39], 0x4000
	v_lshl_add_u64 v[222:223], v[4:5], 0, s[38:39]
	v_lshl_add_u64 v[224:225], v[6:7], 0, s[38:39]
	s_mov_b64 s[38:39], 0x80
	s_waitcnt vmcnt(0) lgkmcnt(0)
	s_barrier
	s_add_i32 m0, s36, 0x0
	s_nop 0
	global_load_lds_dwordx4 v[0:1], off
	v_lshl_add_u64 v[0:1], v[0:1], 0, s[38:39]
	s_add_i32 m0, s36, 0x2000
	s_nop 0
	global_load_lds_dwordx4 v[2:3], off
	v_lshl_add_u64 v[2:3], v[2:3], 0, s[38:39]
	s_add_i32 m0, s36, 0x400
	s_nop 0
	global_load_lds_dwordx4 v[222:223], off
	v_lshl_add_u64 v[222:223], v[222:223], 0, s[38:39]
	s_add_i32 m0, s36, 0x2400
	s_nop 0
	global_load_lds_dwordx4 v[224:225], off
	v_lshl_add_u64 v[224:225], v[224:225], 0, s[38:39]
	s_add_i32 m0, s36, 0x4000
	s_nop 0
	global_load_lds_dwordx4 v[0:1], off
	v_lshl_add_u64 v[0:1], v[0:1], 0, s[38:39]
	s_add_i32 m0, s36, 0x6000
	s_nop 0
	global_load_lds_dwordx4 v[2:3], off
	v_lshl_add_u64 v[2:3], v[2:3], 0, s[38:39]
	s_add_i32 m0, s36, 0x4400
	s_nop 0
	global_load_lds_dwordx4 v[222:223], off
	v_lshl_add_u64 v[222:223], v[222:223], 0, s[38:39]
	s_add_i32 m0, s36, 0x6400
	s_nop 0
	global_load_lds_dwordx4 v[224:225], off
	v_lshl_add_u64 v[224:225], v[224:225], 0, s[38:39]
	s_add_i32 m0, s36, 0x8000
	s_nop 0
	global_load_lds_dwordx4 v[0:1], off
	v_lshl_add_u64 v[0:1], v[0:1], 0, s[38:39]
	s_add_i32 m0, s36, 0xa000
	s_nop 0
	global_load_lds_dwordx4 v[2:3], off
	v_lshl_add_u64 v[2:3], v[2:3], 0, s[38:39]
	s_add_i32 m0, s36, 0x8400
	s_nop 0
	global_load_lds_dwordx4 v[222:223], off
	v_lshl_add_u64 v[222:223], v[222:223], 0, s[38:39]
	s_add_i32 m0, s36, 0xa400
	s_nop 0
	global_load_lds_dwordx4 v[224:225], off
	v_lshl_add_u64 v[224:225], v[224:225], 0, s[38:39]
	s_waitcnt vmcnt(8)
	s_barrier
	s_add_i32 m0, s36, 0xc000
	s_nop 0
	global_load_lds_dwordx4 v[0:1], off
	v_lshl_add_u64 v[0:1], v[0:1], 0, s[38:39]
	s_add_i32 m0, s36, 0xe000
	s_nop 0
	global_load_lds_dwordx4 v[2:3], off
	v_lshl_add_u64 v[2:3], v[2:3], 0, s[38:39]
	s_add_i32 m0, s36, 0xc400
	s_nop 0
	global_load_lds_dwordx4 v[222:223], off
	v_lshl_add_u64 v[222:223], v[222:223], 0, s[38:39]
	s_add_i32 m0, s36, 0xe400
	s_nop 0
	global_load_lds_dwordx4 v[224:225], off
	v_lshl_add_u64 v[224:225], v[224:225], 0, s[38:39]
	ds_read_b128 v[138:141], v218 offset:0
	ds_read_b128 v[142:145], v220 offset:0
	ds_read_b128 v[154:157], v219 offset:0
	ds_read_b128 v[158:161], v219 offset:2048
	ds_read_b128 v[162:165], v219 offset:4096
	ds_read_b128 v[166:169], v219 offset:6144
	ds_read_b128 v[170:173], v221 offset:0
	ds_read_b128 v[174:177], v221 offset:2048
	ds_read_b128 v[178:181], v221 offset:4096
	ds_read_b128 v[182:185], v221 offset:6144
	s_waitcnt lgkmcnt(7)
	v_mfma_f32_16x16x32_bf16 v[44:47], v[138:141], v[154:157], 0
	s_waitcnt lgkmcnt(6)
	v_mfma_f32_16x16x32_bf16 v[40:43], v[138:141], v[158:161], 0
	s_waitcnt lgkmcnt(5)
	v_mfma_f32_16x16x32_bf16 v[36:39], v[138:141], v[162:165], 0
	s_waitcnt lgkmcnt(4)
	v_mfma_f32_16x16x32_bf16 v[32:35], v[138:141], v[166:169], 0
	s_waitcnt lgkmcnt(3)
	v_mfma_f32_16x16x32_bf16 v[44:47], v[142:145], v[170:173], v[44:47]
	s_waitcnt lgkmcnt(2)
	v_mfma_f32_16x16x32_bf16 v[40:43], v[142:145], v[174:177], v[40:43]
	s_waitcnt lgkmcnt(1)
	v_mfma_f32_16x16x32_bf16 v[36:39], v[142:145], v[178:181], v[36:39]
	s_waitcnt lgkmcnt(0)
	v_mfma_f32_16x16x32_bf16 v[32:35], v[142:145], v[182:185], v[32:35]
	s_waitcnt vmcnt(8)
	s_barrier
	s_add_i32 m0, s36, 0x0
	s_nop 0
	global_load_lds_dwordx4 v[0:1], off
	v_lshl_add_u64 v[0:1], v[0:1], 0, s[38:39]
	s_add_i32 m0, s36, 0x2000
	s_nop 0
	global_load_lds_dwordx4 v[2:3], off
	v_lshl_add_u64 v[2:3], v[2:3], 0, s[38:39]
	s_add_i32 m0, s36, 0x400
	s_nop 0
	global_load_lds_dwordx4 v[222:223], off
	v_lshl_add_u64 v[222:223], v[222:223], 0, s[38:39]
	s_add_i32 m0, s36, 0x2400
	s_nop 0
	global_load_lds_dwordx4 v[224:225], off
	v_lshl_add_u64 v[224:225], v[224:225], 0, s[38:39]
	ds_read_b128 v[146:149], v218 offset:16384
	ds_read_b128 v[150:153], v220 offset:16384
	ds_read_b128 v[186:189], v219 offset:16384
	ds_read_b128 v[190:193], v219 offset:18432
	ds_read_b128 v[194:197], v219 offset:20480
	ds_read_b128 v[198:201], v219 offset:22528
	ds_read_b128 v[202:205], v221 offset:16384
	ds_read_b128 v[206:209], v221 offset:18432
	ds_read_b128 v[210:213], v221 offset:20480
	ds_read_b128 v[214:217], v221 offset:22528
	s_waitcnt lgkmcnt(7)
	v_mfma_f32_16x16x32_bf16 v[44:47], v[146:149], v[186:189], v[44:47]
	s_waitcnt lgkmcnt(6)
	v_mfma_f32_16x16x32_bf16 v[40:43], v[146:149], v[190:193], v[40:43]
	s_waitcnt lgkmcnt(5)
	v_mfma_f32_16x16x32_bf16 v[36:39], v[146:149], v[194:197], v[36:39]
	s_waitcnt lgkmcnt(4)
	v_mfma_f32_16x16x32_bf16 v[32:35], v[146:149], v[198:201], v[32:35]
	s_waitcnt lgkmcnt(3)
	v_mfma_f32_16x16x32_bf16 v[44:47], v[150:153], v[202:205], v[44:47]
	s_waitcnt lgkmcnt(2)
	v_mfma_f32_16x16x32_bf16 v[40:43], v[150:153], v[206:209], v[40:43]
	s_waitcnt lgkmcnt(1)
	v_mfma_f32_16x16x32_bf16 v[36:39], v[150:153], v[210:213], v[36:39]
	s_waitcnt lgkmcnt(0)
	v_mfma_f32_16x16x32_bf16 v[32:35], v[150:153], v[214:217], v[32:35]
	s_waitcnt vmcnt(8)
	s_barrier
	s_add_i32 m0, s36, 0x4000
	s_nop 0
	global_load_lds_dwordx4 v[0:1], off
	v_lshl_add_u64 v[0:1], v[0:1], 0, s[38:39]
	s_add_i32 m0, s36, 0x6000
	s_nop 0
	global_load_lds_dwordx4 v[2:3], off
	v_lshl_add_u64 v[2:3], v[2:3], 0, s[38:39]
	s_add_i32 m0, s36, 0x4400
	s_nop 0
	global_load_lds_dwordx4 v[222:223], off
	v_lshl_add_u64 v[222:223], v[222:223], 0, s[38:39]
	s_add_i32 m0, s36, 0x6400
	s_nop 0
	global_load_lds_dwordx4 v[224:225], off
	v_lshl_add_u64 v[224:225], v[224:225], 0, s[38:39]
	ds_read_b128 v[138:141], v218 offset:32768
	ds_read_b128 v[142:145], v220 offset:32768
	ds_read_b128 v[154:157], v219 offset:32768
	ds_read_b128 v[158:161], v219 offset:34816
	ds_read_b128 v[162:165], v219 offset:36864
	ds_read_b128 v[166:169], v219 offset:38912
	ds_read_b128 v[170:173], v221 offset:32768
	ds_read_b128 v[174:177], v221 offset:34816
	ds_read_b128 v[178:181], v221 offset:36864
	ds_read_b128 v[182:185], v221 offset:38912
	s_waitcnt lgkmcnt(7)
	v_mfma_f32_16x16x32_bf16 v[44:47], v[138:141], v[154:157], v[44:47]
	s_waitcnt lgkmcnt(6)
	v_mfma_f32_16x16x32_bf16 v[40:43], v[138:141], v[158:161], v[40:43]
	s_waitcnt lgkmcnt(5)
	v_mfma_f32_16x16x32_bf16 v[36:39], v[138:141], v[162:165], v[36:39]
	s_waitcnt lgkmcnt(4)
	v_mfma_f32_16x16x32_bf16 v[32:35], v[138:141], v[166:169], v[32:35]
	s_waitcnt lgkmcnt(3)
	v_mfma_f32_16x16x32_bf16 v[44:47], v[142:145], v[170:173], v[44:47]
	s_waitcnt lgkmcnt(2)
	v_mfma_f32_16x16x32_bf16 v[40:43], v[142:145], v[174:177], v[40:43]
	s_waitcnt lgkmcnt(1)
	v_mfma_f32_16x16x32_bf16 v[36:39], v[142:145], v[178:181], v[36:39]
	s_waitcnt lgkmcnt(0)
	v_mfma_f32_16x16x32_bf16 v[32:35], v[142:145], v[182:185], v[32:35]
	s_waitcnt vmcnt(8)
	s_barrier
	s_add_i32 m0, s36, 0x8000
	s_nop 0
	global_load_lds_dwordx4 v[0:1], off
	v_lshl_add_u64 v[0:1], v[0:1], 0, s[38:39]
	s_add_i32 m0, s36, 0xa000
	s_nop 0
	global_load_lds_dwordx4 v[2:3], off
	v_lshl_add_u64 v[2:3], v[2:3], 0, s[38:39]
	s_add_i32 m0, s36, 0x8400
	s_nop 0
	global_load_lds_dwordx4 v[222:223], off
	v_lshl_add_u64 v[222:223], v[222:223], 0, s[38:39]
	s_add_i32 m0, s36, 0xa400
	s_nop 0
	global_load_lds_dwordx4 v[224:225], off
	v_lshl_add_u64 v[224:225], v[224:225], 0, s[38:39]
	ds_read_b128 v[146:149], v218 offset:49152
	ds_read_b128 v[150:153], v220 offset:49152
	ds_read_b128 v[186:189], v219 offset:49152
	ds_read_b128 v[190:193], v219 offset:51200
	ds_read_b128 v[194:197], v219 offset:53248
	ds_read_b128 v[198:201], v219 offset:55296
	ds_read_b128 v[202:205], v221 offset:49152
	ds_read_b128 v[206:209], v221 offset:51200
	ds_read_b128 v[210:213], v221 offset:53248
	ds_read_b128 v[214:217], v221 offset:55296
	s_waitcnt lgkmcnt(7)
	v_mfma_f32_16x16x32_bf16 v[44:47], v[146:149], v[186:189], v[44:47]
	s_waitcnt lgkmcnt(6)
	v_mfma_f32_16x16x32_bf16 v[40:43], v[146:149], v[190:193], v[40:43]
	s_waitcnt lgkmcnt(5)
	v_mfma_f32_16x16x32_bf16 v[36:39], v[146:149], v[194:197], v[36:39]
	s_waitcnt lgkmcnt(4)
	v_mfma_f32_16x16x32_bf16 v[32:35], v[146:149], v[198:201], v[32:35]
	s_waitcnt lgkmcnt(3)
	v_mfma_f32_16x16x32_bf16 v[44:47], v[150:153], v[202:205], v[44:47]
	s_waitcnt lgkmcnt(2)
	v_mfma_f32_16x16x32_bf16 v[40:43], v[150:153], v[206:209], v[40:43]
	s_waitcnt lgkmcnt(1)
	v_mfma_f32_16x16x32_bf16 v[36:39], v[150:153], v[210:213], v[36:39]
	s_waitcnt lgkmcnt(0)
	v_mfma_f32_16x16x32_bf16 v[32:35], v[150:153], v[214:217], v[32:35]
	s_waitcnt vmcnt(8)
	s_barrier
	s_add_i32 m0, s36, 0xc000
	s_nop 0
	global_load_lds_dwordx4 v[0:1], off
	v_lshl_add_u64 v[0:1], v[0:1], 0, s[38:39]
	s_add_i32 m0, s36, 0xe000
	s_nop 0
	global_load_lds_dwordx4 v[2:3], off
	v_lshl_add_u64 v[2:3], v[2:3], 0, s[38:39]
	s_add_i32 m0, s36, 0xc400
	s_nop 0
	global_load_lds_dwordx4 v[222:223], off
	v_lshl_add_u64 v[222:223], v[222:223], 0, s[38:39]
	s_add_i32 m0, s36, 0xe400
	s_nop 0
	global_load_lds_dwordx4 v[224:225], off
	v_lshl_add_u64 v[224:225], v[224:225], 0, s[38:39]
	ds_read_b128 v[138:141], v218 offset:0
	ds_read_b128 v[142:145], v220 offset:0
	ds_read_b128 v[154:157], v219 offset:0
	ds_read_b128 v[158:161], v219 offset:2048
	ds_read_b128 v[162:165], v219 offset:4096
	ds_read_b128 v[166:169], v219 offset:6144
	ds_read_b128 v[170:173], v221 offset:0
	ds_read_b128 v[174:177], v221 offset:2048
	ds_read_b128 v[178:181], v221 offset:4096
	ds_read_b128 v[182:185], v221 offset:6144
	s_waitcnt lgkmcnt(7)
	v_mfma_f32_16x16x32_bf16 v[44:47], v[138:141], v[154:157], v[44:47]
	s_waitcnt lgkmcnt(6)
	v_mfma_f32_16x16x32_bf16 v[40:43], v[138:141], v[158:161], v[40:43]
	s_waitcnt lgkmcnt(5)
	v_mfma_f32_16x16x32_bf16 v[36:39], v[138:141], v[162:165], v[36:39]
	s_waitcnt lgkmcnt(4)
	v_mfma_f32_16x16x32_bf16 v[32:35], v[138:141], v[166:169], v[32:35]
	s_waitcnt lgkmcnt(3)
	v_mfma_f32_16x16x32_bf16 v[44:47], v[142:145], v[170:173], v[44:47]
	s_waitcnt lgkmcnt(2)
	v_mfma_f32_16x16x32_bf16 v[40:43], v[142:145], v[174:177], v[40:43]
	s_waitcnt lgkmcnt(1)
	v_mfma_f32_16x16x32_bf16 v[36:39], v[142:145], v[178:181], v[36:39]
	s_waitcnt lgkmcnt(0)
	v_mfma_f32_16x16x32_bf16 v[32:35], v[142:145], v[182:185], v[32:35]
	s_waitcnt vmcnt(8)
	s_barrier
	s_add_i32 m0, s36, 0x0
	s_nop 0
	global_load_lds_dwordx4 v[0:1], off
	v_lshl_add_u64 v[0:1], v[0:1], 0, s[38:39]
	s_add_i32 m0, s36, 0x2000
	s_nop 0
	global_load_lds_dwordx4 v[2:3], off
	v_lshl_add_u64 v[2:3], v[2:3], 0, s[38:39]
	s_add_i32 m0, s36, 0x400
	s_nop 0
	global_load_lds_dwordx4 v[222:223], off
	v_lshl_add_u64 v[222:223], v[222:223], 0, s[38:39]
	s_add_i32 m0, s36, 0x2400
	s_nop 0
	global_load_lds_dwordx4 v[224:225], off
	v_lshl_add_u64 v[224:225], v[224:225], 0, s[38:39]
	ds_read_b128 v[146:149], v218 offset:16384
	ds_read_b128 v[150:153], v220 offset:16384
	ds_read_b128 v[186:189], v219 offset:16384
	ds_read_b128 v[190:193], v219 offset:18432
	ds_read_b128 v[194:197], v219 offset:20480
	ds_read_b128 v[198:201], v219 offset:22528
	ds_read_b128 v[202:205], v221 offset:16384
	ds_read_b128 v[206:209], v221 offset:18432
	ds_read_b128 v[210:213], v221 offset:20480
	ds_read_b128 v[214:217], v221 offset:22528
	s_waitcnt lgkmcnt(7)
	v_mfma_f32_16x16x32_bf16 v[44:47], v[146:149], v[186:189], v[44:47]
	s_waitcnt lgkmcnt(6)
	v_mfma_f32_16x16x32_bf16 v[40:43], v[146:149], v[190:193], v[40:43]
	s_waitcnt lgkmcnt(5)
	v_mfma_f32_16x16x32_bf16 v[36:39], v[146:149], v[194:197], v[36:39]
	s_waitcnt lgkmcnt(4)
	v_mfma_f32_16x16x32_bf16 v[32:35], v[146:149], v[198:201], v[32:35]
	s_waitcnt lgkmcnt(3)
	v_mfma_f32_16x16x32_bf16 v[44:47], v[150:153], v[202:205], v[44:47]
	s_waitcnt lgkmcnt(2)
	v_mfma_f32_16x16x32_bf16 v[40:43], v[150:153], v[206:209], v[40:43]
	s_waitcnt lgkmcnt(1)
	v_mfma_f32_16x16x32_bf16 v[36:39], v[150:153], v[210:213], v[36:39]
	s_waitcnt lgkmcnt(0)
	v_mfma_f32_16x16x32_bf16 v[32:35], v[150:153], v[214:217], v[32:35]
	s_waitcnt vmcnt(8)
	s_barrier
	s_add_i32 m0, s36, 0x4000
	s_nop 0
	global_load_lds_dwordx4 v[0:1], off
	v_lshl_add_u64 v[0:1], v[0:1], 0, s[38:39]
	s_add_i32 m0, s36, 0x6000
	s_nop 0
	global_load_lds_dwordx4 v[2:3], off
	v_lshl_add_u64 v[2:3], v[2:3], 0, s[38:39]
	s_add_i32 m0, s36, 0x4400
	s_nop 0
	global_load_lds_dwordx4 v[222:223], off
	v_lshl_add_u64 v[222:223], v[222:223], 0, s[38:39]
	s_add_i32 m0, s36, 0x6400
	s_nop 0
	global_load_lds_dwordx4 v[224:225], off
	v_lshl_add_u64 v[224:225], v[224:225], 0, s[38:39]
	ds_read_b128 v[138:141], v218 offset:32768
	ds_read_b128 v[142:145], v220 offset:32768
	ds_read_b128 v[154:157], v219 offset:32768
	ds_read_b128 v[158:161], v219 offset:34816
	ds_read_b128 v[162:165], v219 offset:36864
	ds_read_b128 v[166:169], v219 offset:38912
	ds_read_b128 v[170:173], v221 offset:32768
	ds_read_b128 v[174:177], v221 offset:34816
	ds_read_b128 v[178:181], v221 offset:36864
	ds_read_b128 v[182:185], v221 offset:38912
	s_waitcnt lgkmcnt(7)
	v_mfma_f32_16x16x32_bf16 v[44:47], v[138:141], v[154:157], v[44:47]
	s_waitcnt lgkmcnt(6)
	v_mfma_f32_16x16x32_bf16 v[40:43], v[138:141], v[158:161], v[40:43]
	s_waitcnt lgkmcnt(5)
	v_mfma_f32_16x16x32_bf16 v[36:39], v[138:141], v[162:165], v[36:39]
	s_waitcnt lgkmcnt(4)
	v_mfma_f32_16x16x32_bf16 v[32:35], v[138:141], v[166:169], v[32:35]
	s_waitcnt lgkmcnt(3)
	v_mfma_f32_16x16x32_bf16 v[44:47], v[142:145], v[170:173], v[44:47]
	s_waitcnt lgkmcnt(2)
	v_mfma_f32_16x16x32_bf16 v[40:43], v[142:145], v[174:177], v[40:43]
	s_waitcnt lgkmcnt(1)
	v_mfma_f32_16x16x32_bf16 v[36:39], v[142:145], v[178:181], v[36:39]
	s_waitcnt lgkmcnt(0)
	v_mfma_f32_16x16x32_bf16 v[32:35], v[142:145], v[182:185], v[32:35]
	s_waitcnt vmcnt(8)
	s_barrier
	s_add_i32 m0, s36, 0x8000
	s_nop 0
	global_load_lds_dwordx4 v[0:1], off
	v_lshl_add_u64 v[0:1], v[0:1], 0, s[38:39]
	s_add_i32 m0, s36, 0xa000
	s_nop 0
	global_load_lds_dwordx4 v[2:3], off
	v_lshl_add_u64 v[2:3], v[2:3], 0, s[38:39]
	s_add_i32 m0, s36, 0x8400
	s_nop 0
	global_load_lds_dwordx4 v[222:223], off
	v_lshl_add_u64 v[222:223], v[222:223], 0, s[38:39]
	s_add_i32 m0, s36, 0xa400
	s_nop 0
	global_load_lds_dwordx4 v[224:225], off
	v_lshl_add_u64 v[224:225], v[224:225], 0, s[38:39]
	ds_read_b128 v[146:149], v218 offset:49152
	ds_read_b128 v[150:153], v220 offset:49152
	ds_read_b128 v[186:189], v219 offset:49152
	ds_read_b128 v[190:193], v219 offset:51200
	ds_read_b128 v[194:197], v219 offset:53248
	ds_read_b128 v[198:201], v219 offset:55296
	ds_read_b128 v[202:205], v221 offset:49152
	ds_read_b128 v[206:209], v221 offset:51200
	ds_read_b128 v[210:213], v221 offset:53248
	ds_read_b128 v[214:217], v221 offset:55296
	s_waitcnt lgkmcnt(7)
	v_mfma_f32_16x16x32_bf16 v[44:47], v[146:149], v[186:189], v[44:47]
	s_waitcnt lgkmcnt(6)
	v_mfma_f32_16x16x32_bf16 v[40:43], v[146:149], v[190:193], v[40:43]
	s_waitcnt lgkmcnt(5)
	v_mfma_f32_16x16x32_bf16 v[36:39], v[146:149], v[194:197], v[36:39]
	s_waitcnt lgkmcnt(4)
	v_mfma_f32_16x16x32_bf16 v[32:35], v[146:149], v[198:201], v[32:35]
	s_waitcnt lgkmcnt(3)
	v_mfma_f32_16x16x32_bf16 v[44:47], v[150:153], v[202:205], v[44:47]
	s_waitcnt lgkmcnt(2)
	v_mfma_f32_16x16x32_bf16 v[40:43], v[150:153], v[206:209], v[40:43]
	s_waitcnt lgkmcnt(1)
	v_mfma_f32_16x16x32_bf16 v[36:39], v[150:153], v[210:213], v[36:39]
	s_waitcnt lgkmcnt(0)
	v_mfma_f32_16x16x32_bf16 v[32:35], v[150:153], v[214:217], v[32:35]
	s_waitcnt vmcnt(8)
	s_barrier
	s_add_i32 m0, s36, 0xc000
	s_nop 0
	global_load_lds_dwordx4 v[0:1], off
	v_lshl_add_u64 v[0:1], v[0:1], 0, s[38:39]
	s_add_i32 m0, s36, 0xe000
	s_nop 0
	global_load_lds_dwordx4 v[2:3], off
	v_lshl_add_u64 v[2:3], v[2:3], 0, s[38:39]
	s_add_i32 m0, s36, 0xc400
	s_nop 0
	global_load_lds_dwordx4 v[222:223], off
	v_lshl_add_u64 v[222:223], v[222:223], 0, s[38:39]
	s_add_i32 m0, s36, 0xe400
	s_nop 0
	global_load_lds_dwordx4 v[224:225], off
	v_lshl_add_u64 v[224:225], v[224:225], 0, s[38:39]
	ds_read_b128 v[138:141], v218 offset:0
	ds_read_b128 v[142:145], v220 offset:0
	ds_read_b128 v[154:157], v219 offset:0
	ds_read_b128 v[158:161], v219 offset:2048
	ds_read_b128 v[162:165], v219 offset:4096
	ds_read_b128 v[166:169], v219 offset:6144
	ds_read_b128 v[170:173], v221 offset:0
	ds_read_b128 v[174:177], v221 offset:2048
	ds_read_b128 v[178:181], v221 offset:4096
	ds_read_b128 v[182:185], v221 offset:6144
	s_waitcnt lgkmcnt(7)
	v_mfma_f32_16x16x32_bf16 v[44:47], v[138:141], v[154:157], v[44:47]
	s_waitcnt lgkmcnt(6)
	v_mfma_f32_16x16x32_bf16 v[40:43], v[138:141], v[158:161], v[40:43]
	s_waitcnt lgkmcnt(5)
	v_mfma_f32_16x16x32_bf16 v[36:39], v[138:141], v[162:165], v[36:39]
	s_waitcnt lgkmcnt(4)
	v_mfma_f32_16x16x32_bf16 v[32:35], v[138:141], v[166:169], v[32:35]
	s_waitcnt lgkmcnt(3)
	v_mfma_f32_16x16x32_bf16 v[44:47], v[142:145], v[170:173], v[44:47]
	s_waitcnt lgkmcnt(2)
	v_mfma_f32_16x16x32_bf16 v[40:43], v[142:145], v[174:177], v[40:43]
	s_waitcnt lgkmcnt(1)
	v_mfma_f32_16x16x32_bf16 v[36:39], v[142:145], v[178:181], v[36:39]
	s_waitcnt lgkmcnt(0)
	v_mfma_f32_16x16x32_bf16 v[32:35], v[142:145], v[182:185], v[32:35]
	s_waitcnt vmcnt(8)
	s_barrier
	s_add_i32 m0, s36, 0x0
	s_nop 0
	global_load_lds_dwordx4 v[0:1], off
	v_lshl_add_u64 v[0:1], v[0:1], 0, s[38:39]
	s_add_i32 m0, s36, 0x2000
	s_nop 0
	global_load_lds_dwordx4 v[2:3], off
	v_lshl_add_u64 v[2:3], v[2:3], 0, s[38:39]
	s_add_i32 m0, s36, 0x400
	s_nop 0
	global_load_lds_dwordx4 v[222:223], off
	v_lshl_add_u64 v[222:223], v[222:223], 0, s[38:39]
	s_add_i32 m0, s36, 0x2400
	s_nop 0
	global_load_lds_dwordx4 v[224:225], off
	v_lshl_add_u64 v[224:225], v[224:225], 0, s[38:39]
	ds_read_b128 v[146:149], v218 offset:16384
	ds_read_b128 v[150:153], v220 offset:16384
	ds_read_b128 v[186:189], v219 offset:16384
	ds_read_b128 v[190:193], v219 offset:18432
	ds_read_b128 v[194:197], v219 offset:20480
	ds_read_b128 v[198:201], v219 offset:22528
	ds_read_b128 v[202:205], v221 offset:16384
	ds_read_b128 v[206:209], v221 offset:18432
	ds_read_b128 v[210:213], v221 offset:20480
	ds_read_b128 v[214:217], v221 offset:22528
	s_waitcnt lgkmcnt(7)
	v_mfma_f32_16x16x32_bf16 v[44:47], v[146:149], v[186:189], v[44:47]
	s_waitcnt lgkmcnt(6)
	v_mfma_f32_16x16x32_bf16 v[40:43], v[146:149], v[190:193], v[40:43]
	s_waitcnt lgkmcnt(5)
	v_mfma_f32_16x16x32_bf16 v[36:39], v[146:149], v[194:197], v[36:39]
	s_waitcnt lgkmcnt(4)
	v_mfma_f32_16x16x32_bf16 v[32:35], v[146:149], v[198:201], v[32:35]
	s_waitcnt lgkmcnt(3)
	v_mfma_f32_16x16x32_bf16 v[44:47], v[150:153], v[202:205], v[44:47]
	s_waitcnt lgkmcnt(2)
	v_mfma_f32_16x16x32_bf16 v[40:43], v[150:153], v[206:209], v[40:43]
	s_waitcnt lgkmcnt(1)
	v_mfma_f32_16x16x32_bf16 v[36:39], v[150:153], v[210:213], v[36:39]
	s_waitcnt lgkmcnt(0)
	v_mfma_f32_16x16x32_bf16 v[32:35], v[150:153], v[214:217], v[32:35]
	s_waitcnt vmcnt(8)
	s_barrier
	s_add_i32 m0, s36, 0x4000
	s_nop 0
	global_load_lds_dwordx4 v[0:1], off
	v_lshl_add_u64 v[0:1], v[0:1], 0, s[38:39]
	s_add_i32 m0, s36, 0x6000
	s_nop 0
	global_load_lds_dwordx4 v[2:3], off
	v_lshl_add_u64 v[2:3], v[2:3], 0, s[38:39]
	s_add_i32 m0, s36, 0x4400
	s_nop 0
	global_load_lds_dwordx4 v[222:223], off
	v_lshl_add_u64 v[222:223], v[222:223], 0, s[38:39]
	s_add_i32 m0, s36, 0x6400
	s_nop 0
	global_load_lds_dwordx4 v[224:225], off
	v_lshl_add_u64 v[224:225], v[224:225], 0, s[38:39]
	ds_read_b128 v[138:141], v218 offset:32768
	ds_read_b128 v[142:145], v220 offset:32768
	ds_read_b128 v[154:157], v219 offset:32768
	ds_read_b128 v[158:161], v219 offset:34816
	ds_read_b128 v[162:165], v219 offset:36864
	ds_read_b128 v[166:169], v219 offset:38912
	ds_read_b128 v[170:173], v221 offset:32768
	ds_read_b128 v[174:177], v221 offset:34816
	ds_read_b128 v[178:181], v221 offset:36864
	ds_read_b128 v[182:185], v221 offset:38912
	s_waitcnt lgkmcnt(7)
	v_mfma_f32_16x16x32_bf16 v[44:47], v[138:141], v[154:157], v[44:47]
	s_waitcnt lgkmcnt(6)
	v_mfma_f32_16x16x32_bf16 v[40:43], v[138:141], v[158:161], v[40:43]
	s_waitcnt lgkmcnt(5)
	v_mfma_f32_16x16x32_bf16 v[36:39], v[138:141], v[162:165], v[36:39]
	s_waitcnt lgkmcnt(4)
	v_mfma_f32_16x16x32_bf16 v[32:35], v[138:141], v[166:169], v[32:35]
	s_waitcnt lgkmcnt(3)
	v_mfma_f32_16x16x32_bf16 v[44:47], v[142:145], v[170:173], v[44:47]
	s_waitcnt lgkmcnt(2)
	v_mfma_f32_16x16x32_bf16 v[40:43], v[142:145], v[174:177], v[40:43]
	s_waitcnt lgkmcnt(1)
	v_mfma_f32_16x16x32_bf16 v[36:39], v[142:145], v[178:181], v[36:39]
	s_waitcnt lgkmcnt(0)
	v_mfma_f32_16x16x32_bf16 v[32:35], v[142:145], v[182:185], v[32:35]
	s_waitcnt vmcnt(8)
	s_barrier
	s_add_i32 m0, s36, 0x8000
	s_nop 0
	global_load_lds_dwordx4 v[0:1], off
	v_lshl_add_u64 v[0:1], v[0:1], 0, s[38:39]
	s_add_i32 m0, s36, 0xa000
	s_nop 0
	global_load_lds_dwordx4 v[2:3], off
	v_lshl_add_u64 v[2:3], v[2:3], 0, s[38:39]
	s_add_i32 m0, s36, 0x8400
	s_nop 0
	global_load_lds_dwordx4 v[222:223], off
	v_lshl_add_u64 v[222:223], v[222:223], 0, s[38:39]
	s_add_i32 m0, s36, 0xa400
	s_nop 0
	global_load_lds_dwordx4 v[224:225], off
	v_lshl_add_u64 v[224:225], v[224:225], 0, s[38:39]
	ds_read_b128 v[146:149], v218 offset:49152
	ds_read_b128 v[150:153], v220 offset:49152
	ds_read_b128 v[186:189], v219 offset:49152
	ds_read_b128 v[190:193], v219 offset:51200
	ds_read_b128 v[194:197], v219 offset:53248
	ds_read_b128 v[198:201], v219 offset:55296
	ds_read_b128 v[202:205], v221 offset:49152
	ds_read_b128 v[206:209], v221 offset:51200
	ds_read_b128 v[210:213], v221 offset:53248
	ds_read_b128 v[214:217], v221 offset:55296
	s_waitcnt lgkmcnt(7)
	v_mfma_f32_16x16x32_bf16 v[44:47], v[146:149], v[186:189], v[44:47]
	s_waitcnt lgkmcnt(6)
	v_mfma_f32_16x16x32_bf16 v[40:43], v[146:149], v[190:193], v[40:43]
	s_waitcnt lgkmcnt(5)
	v_mfma_f32_16x16x32_bf16 v[36:39], v[146:149], v[194:197], v[36:39]
	s_waitcnt lgkmcnt(4)
	v_mfma_f32_16x16x32_bf16 v[32:35], v[146:149], v[198:201], v[32:35]
	s_waitcnt lgkmcnt(3)
	v_mfma_f32_16x16x32_bf16 v[44:47], v[150:153], v[202:205], v[44:47]
	s_waitcnt lgkmcnt(2)
	v_mfma_f32_16x16x32_bf16 v[40:43], v[150:153], v[206:209], v[40:43]
	s_waitcnt lgkmcnt(1)
	v_mfma_f32_16x16x32_bf16 v[36:39], v[150:153], v[210:213], v[36:39]
	s_waitcnt lgkmcnt(0)
	v_mfma_f32_16x16x32_bf16 v[32:35], v[150:153], v[214:217], v[32:35]
	s_waitcnt vmcnt(8)
	s_barrier
	s_add_i32 m0, s36, 0xc000
	s_nop 0
	global_load_lds_dwordx4 v[0:1], off
	v_lshl_add_u64 v[0:1], v[0:1], 0, s[38:39]
	s_add_i32 m0, s36, 0xe000
	s_nop 0
	global_load_lds_dwordx4 v[2:3], off
	v_lshl_add_u64 v[2:3], v[2:3], 0, s[38:39]
	s_add_i32 m0, s36, 0xc400
	s_nop 0
	global_load_lds_dwordx4 v[222:223], off
	v_lshl_add_u64 v[222:223], v[222:223], 0, s[38:39]
	s_add_i32 m0, s36, 0xe400
	s_nop 0
	global_load_lds_dwordx4 v[224:225], off
	v_lshl_add_u64 v[224:225], v[224:225], 0, s[38:39]
	ds_read_b128 v[138:141], v218 offset:0
	ds_read_b128 v[142:145], v220 offset:0
	ds_read_b128 v[154:157], v219 offset:0
	ds_read_b128 v[158:161], v219 offset:2048
	ds_read_b128 v[162:165], v219 offset:4096
	ds_read_b128 v[166:169], v219 offset:6144
	ds_read_b128 v[170:173], v221 offset:0
	ds_read_b128 v[174:177], v221 offset:2048
	ds_read_b128 v[178:181], v221 offset:4096
	ds_read_b128 v[182:185], v221 offset:6144
	s_waitcnt lgkmcnt(7)
	v_mfma_f32_16x16x32_bf16 v[44:47], v[138:141], v[154:157], v[44:47]
	s_waitcnt lgkmcnt(6)
	v_mfma_f32_16x16x32_bf16 v[40:43], v[138:141], v[158:161], v[40:43]
	s_waitcnt lgkmcnt(5)
	v_mfma_f32_16x16x32_bf16 v[36:39], v[138:141], v[162:165], v[36:39]
	s_waitcnt lgkmcnt(4)
	v_mfma_f32_16x16x32_bf16 v[32:35], v[138:141], v[166:169], v[32:35]
	s_waitcnt lgkmcnt(3)
	v_mfma_f32_16x16x32_bf16 v[44:47], v[142:145], v[170:173], v[44:47]
	s_waitcnt lgkmcnt(2)
	v_mfma_f32_16x16x32_bf16 v[40:43], v[142:145], v[174:177], v[40:43]
	s_waitcnt lgkmcnt(1)
	v_mfma_f32_16x16x32_bf16 v[36:39], v[142:145], v[178:181], v[36:39]
	s_waitcnt lgkmcnt(0)
	v_mfma_f32_16x16x32_bf16 v[32:35], v[142:145], v[182:185], v[32:35]
	s_waitcnt vmcnt(8)
	s_barrier
	ds_read_b128 v[146:149], v218 offset:16384
	ds_read_b128 v[150:153], v220 offset:16384
	ds_read_b128 v[186:189], v219 offset:16384
	ds_read_b128 v[190:193], v219 offset:18432
	ds_read_b128 v[194:197], v219 offset:20480
	ds_read_b128 v[198:201], v219 offset:22528
	ds_read_b128 v[202:205], v221 offset:16384
	ds_read_b128 v[206:209], v221 offset:18432
	ds_read_b128 v[210:213], v221 offset:20480
	ds_read_b128 v[214:217], v221 offset:22528
	s_waitcnt lgkmcnt(7)
	v_mfma_f32_16x16x32_bf16 v[44:47], v[146:149], v[186:189], v[44:47]
	s_waitcnt lgkmcnt(6)
	v_mfma_f32_16x16x32_bf16 v[40:43], v[146:149], v[190:193], v[40:43]
	s_waitcnt lgkmcnt(5)
	v_mfma_f32_16x16x32_bf16 v[36:39], v[146:149], v[194:197], v[36:39]
	s_waitcnt lgkmcnt(4)
	v_mfma_f32_16x16x32_bf16 v[32:35], v[146:149], v[198:201], v[32:35]
	s_waitcnt lgkmcnt(3)
	v_mfma_f32_16x16x32_bf16 v[44:47], v[150:153], v[202:205], v[44:47]
	s_waitcnt lgkmcnt(2)
	v_mfma_f32_16x16x32_bf16 v[40:43], v[150:153], v[206:209], v[40:43]
	s_waitcnt lgkmcnt(1)
	v_mfma_f32_16x16x32_bf16 v[36:39], v[150:153], v[210:213], v[36:39]
	s_waitcnt lgkmcnt(0)
	v_mfma_f32_16x16x32_bf16 v[32:35], v[150:153], v[214:217], v[32:35]
	s_waitcnt vmcnt(4)
	s_barrier
	ds_read_b128 v[138:141], v218 offset:32768
	ds_read_b128 v[142:145], v220 offset:32768
	ds_read_b128 v[154:157], v219 offset:32768
	ds_read_b128 v[158:161], v219 offset:34816
	ds_read_b128 v[162:165], v219 offset:36864
	ds_read_b128 v[166:169], v219 offset:38912
	ds_read_b128 v[170:173], v221 offset:32768
	ds_read_b128 v[174:177], v221 offset:34816
	ds_read_b128 v[178:181], v221 offset:36864
	ds_read_b128 v[182:185], v221 offset:38912
	s_waitcnt lgkmcnt(7)
	v_mfma_f32_16x16x32_bf16 v[44:47], v[138:141], v[154:157], v[44:47]
	s_waitcnt lgkmcnt(6)
	v_mfma_f32_16x16x32_bf16 v[40:43], v[138:141], v[158:161], v[40:43]
	s_waitcnt lgkmcnt(5)
	v_mfma_f32_16x16x32_bf16 v[36:39], v[138:141], v[162:165], v[36:39]
	s_waitcnt lgkmcnt(4)
	v_mfma_f32_16x16x32_bf16 v[32:35], v[138:141], v[166:169], v[32:35]
	s_waitcnt lgkmcnt(3)
	v_mfma_f32_16x16x32_bf16 v[44:47], v[142:145], v[170:173], v[44:47]
	s_waitcnt lgkmcnt(2)
	v_mfma_f32_16x16x32_bf16 v[40:43], v[142:145], v[174:177], v[40:43]
	s_waitcnt lgkmcnt(1)
	v_mfma_f32_16x16x32_bf16 v[36:39], v[142:145], v[178:181], v[36:39]
	s_waitcnt lgkmcnt(0)
	v_mfma_f32_16x16x32_bf16 v[32:35], v[142:145], v[182:185], v[32:35]
	s_waitcnt vmcnt(0)
	s_barrier
	ds_read_b128 v[146:149], v218 offset:49152
	ds_read_b128 v[150:153], v220 offset:49152
	ds_read_b128 v[186:189], v219 offset:49152
	ds_read_b128 v[190:193], v219 offset:51200
	ds_read_b128 v[194:197], v219 offset:53248
	ds_read_b128 v[198:201], v219 offset:55296
	ds_read_b128 v[202:205], v221 offset:49152
	ds_read_b128 v[206:209], v221 offset:51200
	ds_read_b128 v[210:213], v221 offset:53248
	ds_read_b128 v[214:217], v221 offset:55296
	s_waitcnt lgkmcnt(7)
	v_mfma_f32_16x16x32_bf16 v[44:47], v[146:149], v[186:189], v[44:47]
	s_waitcnt lgkmcnt(6)
	v_mfma_f32_16x16x32_bf16 v[40:43], v[146:149], v[190:193], v[40:43]
	s_waitcnt lgkmcnt(5)
	v_mfma_f32_16x16x32_bf16 v[36:39], v[146:149], v[194:197], v[36:39]
	s_waitcnt lgkmcnt(4)
	v_mfma_f32_16x16x32_bf16 v[32:35], v[146:149], v[198:201], v[32:35]
	s_waitcnt lgkmcnt(3)
	v_mfma_f32_16x16x32_bf16 v[44:47], v[150:153], v[202:205], v[44:47]
	s_waitcnt lgkmcnt(2)
	v_mfma_f32_16x16x32_bf16 v[40:43], v[150:153], v[206:209], v[40:43]
	s_waitcnt lgkmcnt(1)
	v_mfma_f32_16x16x32_bf16 v[36:39], v[150:153], v[210:213], v[36:39]
	s_waitcnt lgkmcnt(0)
	v_mfma_f32_16x16x32_bf16 v[32:35], v[150:153], v[214:217], v[32:35]
	s_nop 7
	s_nop 1
	s_cmp_lt_i32 s44, 36
	s_cbranch_scc0 .LBB0_312
	s_cmp_lt_i32 s44, 18
	s_cbranch_scc0 .LBB0_309
	s_cmp_lg_u32 s4, 1
	s_cbranch_scc1 .LBB0_280
	v_readlane_b32 s64, v242, 10
	s_cmp_lt_i32 s44, 14
	v_readlane_b32 s68, v242, 14
	v_readlane_b32 s69, v242, 15
	v_readlane_b32 s70, v242, 16
	v_readlane_b32 s71, v242, 17
	s_cselect_b32 s3, s69, s71
	s_cselect_b32 s2, s68, s70
	v_lshlrev_b32_e32 v1, 2, v50
	v_lshl_or_b32 v3, v8, 2, v129
	global_load_dword v0, v1, s[2:3]
	global_load_dword v2, v1, s[2:3] offset:64
	global_load_dword v4, v1, s[2:3] offset:128
	global_load_dword v6, v3, s[2:3]
	v_mov_b32_e32 v8, v44
	v_mov_b32_e32 v9, v40
	v_mov_b32_e32 v10, v36
	v_mov_b32_e32 v11, v32
	v_mov_b32_e32 v12, v45
	v_mov_b32_e32 v13, v41
	v_mov_b32_e32 v16, v46
	v_mov_b32_e32 v17, v42
	v_mov_b32_e32 v20, v47
	v_mov_b32_e32 v21, v43
	v_pk_mul_f32 v[8:9], v[8:9], v[8:9]
	v_mov_b32_e32 v14, v37
	v_mov_b32_e32 v15, v33
	v_mov_b32_e32 v18, v38
	v_mov_b32_e32 v19, v34
	v_mov_b32_e32 v22, v39
	v_mov_b32_e32 v23, v35
	v_pk_mul_f32 v[10:11], v[10:11], v[10:11]
	v_pk_mul_f32 v[12:13], v[12:13], v[12:13]
	v_pk_mul_f32 v[16:17], v[16:17], v[16:17]
	v_pk_mul_f32 v[20:21], v[20:21], v[20:21]
	v_add_f32_e32 v1, v8, v9
	v_pk_mul_f32 v[14:15], v[14:15], v[14:15]
	v_pk_mul_f32 v[18:19], v[18:19], v[18:19]
	v_pk_mul_f32 v[22:23], v[22:23], v[22:23]
	v_add_f32_e32 v3, v12, v13
	v_add_f32_e32 v5, v16, v17
	v_add_f32_e32 v7, v20, v21
	v_add_f32_e32 v1, v10, v1
	v_add_f32_e32 v3, v14, v3
	v_add_f32_e32 v5, v18, v5
	v_add_f32_e32 v7, v22, v7
	v_add_f32_e32 v1, v1, v11
	v_add_f32_e32 v3, v3, v15
	v_add_f32_e32 v5, v5, v19
	v_add_f32_e32 v7, v7, v23
	v_add_f32_dpp v1, v1, v1 quad_perm:[1,0,3,2] row_mask:0xf bank_mask:0xf bound_ctrl:1
	v_add_f32_dpp v3, v3, v3 quad_perm:[1,0,3,2] row_mask:0xf bank_mask:0xf bound_ctrl:1
	v_add_f32_dpp v5, v5, v5 quad_perm:[1,0,3,2] row_mask:0xf bank_mask:0xf bound_ctrl:1
	v_add_f32_dpp v7, v7, v7 quad_perm:[1,0,3,2] row_mask:0xf bank_mask:0xf bound_ctrl:1
	v_add_f32_dpp v1, v1, v1 quad_perm:[2,3,0,1] row_mask:0xf bank_mask:0xf bound_ctrl:1
	v_add_f32_dpp v3, v3, v3 quad_perm:[2,3,0,1] row_mask:0xf bank_mask:0xf bound_ctrl:1
	v_add_f32_dpp v5, v5, v5 quad_perm:[2,3,0,1] row_mask:0xf bank_mask:0xf bound_ctrl:1
	v_add_f32_dpp v7, v7, v7 quad_perm:[2,3,0,1] row_mask:0xf bank_mask:0xf bound_ctrl:1
	v_add_f32_dpp v1, v1, v1 row_ror:4 row_mask:0xf bank_mask:0xf bound_ctrl:1
	v_add_f32_dpp v3, v3, v3 row_ror:4 row_mask:0xf bank_mask:0xf bound_ctrl:1
	v_add_f32_dpp v5, v5, v5 row_ror:4 row_mask:0xf bank_mask:0xf bound_ctrl:1
	v_add_f32_dpp v7, v7, v7 row_ror:4 row_mask:0xf bank_mask:0xf bound_ctrl:1
	v_add_f32_dpp v1, v1, v1 row_ror:8 row_mask:0xf bank_mask:0xf bound_ctrl:1
	v_add_f32_dpp v3, v3, v3 row_ror:8 row_mask:0xf bank_mask:0xf bound_ctrl:1
	v_add_f32_dpp v5, v5, v5 row_ror:8 row_mask:0xf bank_mask:0xf bound_ctrl:1
	v_add_f32_dpp v7, v7, v7 row_ror:8 row_mask:0xf bank_mask:0xf bound_ctrl:1
	v_fmamk_f32 v1, v1, 0x3c800000, v124
	v_fmamk_f32 v3, v3, 0x3c800000, v124
	v_fmamk_f32 v5, v5, 0x3c800000, v124
	v_rsq_f32_e32 v8, v1
	v_fmamk_f32 v1, v7, 0x3c800000, v124
	v_rsq_f32_e32 v9, v3
	v_rsq_f32_e32 v10, v5
	v_rsq_f32_e32 v11, v1
	v_readlane_b32 s65, v242, 11
	v_readlane_b32 s66, v242, 12
	v_readlane_b32 s67, v242, 13
	v_readlane_b32 s72, v242, 18
	v_readlane_b32 s73, v242, 19
	v_readlane_b32 s74, v242, 20
	v_readlane_b32 s75, v242, 21
	v_readlane_b32 s76, v242, 22
	v_readlane_b32 s77, v242, 23
	v_readlane_b32 s78, v242, 24
	v_readlane_b32 s79, v242, 25
	v_readlane_b32 s64, v241, 29
	v_readlane_b32 s68, v241, 33
	v_readlane_b32 s69, v241, 34
	v_readlane_b32 s68, v241, 45
	v_readlane_b32 s78, v241, 43
	s_waitcnt vmcnt(3)
	v_pk_mul_f32 v[12:13], v[0:1], v[8:9] op_sel_hi:[0,1]
	s_waitcnt vmcnt(2)
	v_pk_mul_f32 v[14:15], v[2:3], v[8:9] op_sel_hi:[0,1]
	s_waitcnt vmcnt(1)
	v_pk_mul_f32 v[16:17], v[4:5], v[8:9] op_sel_hi:[0,1]
	s_waitcnt vmcnt(0)
	v_pk_mul_f32 v[18:19], v[6:7], v[8:9] op_sel_hi:[0,1]
	v_pk_mul_f32 v[20:21], v[0:1], v[10:11] op_sel_hi:[0,1]
	v_pk_mul_f32 v[22:23], v[2:3], v[10:11] op_sel_hi:[0,1]
	v_pk_mul_f32 v[24:25], v[4:5], v[10:11] op_sel_hi:[0,1]
	v_pk_mul_f32 v[26:27], v[6:7], v[10:11] op_sel_hi:[0,1]
	v_readlane_b32 s79, v241, 44
	v_readlane_b32 s69, v241, 46
	v_pk_mul_f32 v[0:1], v[44:45], v[12:13]
	v_pk_mul_f32 v[4:5], v[40:41], v[14:15]
	v_pk_mul_f32 v[8:9], v[36:37], v[16:17]
	v_pk_mul_f32 v[12:13], v[32:33], v[18:19]
	v_pk_mul_f32 v[2:3], v[46:47], v[20:21]
	v_pk_mul_f32 v[6:7], v[42:43], v[22:23]
	v_pk_mul_f32 v[10:11], v[38:39], v[24:25]
	v_pk_mul_f32 v[14:15], v[34:35], v[26:27]
	v_readlane_b32 s65, v241, 30
	v_readlane_b32 s66, v241, 31
	v_readlane_b32 s67, v241, 32
	v_readlane_b32 s70, v241, 35
	v_readlane_b32 s71, v241, 36
	v_readlane_b32 s72, v241, 37
	v_readlane_b32 s73, v241, 38
	v_readlane_b32 s74, v241, 39
	v_readlane_b32 s75, v241, 40
	v_readlane_b32 s76, v241, 41
	v_readlane_b32 s77, v241, 42
	s_branch .LBB0_281

.LBB0_1378:
	s_mov_b32 s33, s82
	s_add_i32 s82, s82, s66
	s_cmpk_lt_i32 s82, 0x641
	s_cselect_b64 s[0:1], -1, 0
	s_and_b64 vcc, exec, s[0:1]
	s_cbranch_vccnz .LBB0_1484
	s_lshl_b32 s0, s33, 2
	s_sub_i32 s2, 0x1900, s0
	s_cmp_le_i32 s2, s66
	s_mov_b64 s[0:1], -1
	s_cbranch_scc0 .LBB0_1484
	s_cmp_ge_i32 s40, s2
	s_cbranch_scc1 .LBB0_1483
	s_add_i32 s0, s33, s41
	s_ashr_i32 s1, s0, 5
	s_mul_hi_i32 s2, s1, 0x66666667
	s_lshr_b32 s3, s2, 31
	s_ashr_i32 s2, s2, 1
	s_add_i32 s3, s2, s3
	s_mul_i32 s2, s3, 5
	s_sub_i32 s2, s1, s2
	s_lshl_b32 s1, s3, 10
	s_lshl_b32 s3, s0, 5
	s_lshl_b32 s0, s0, 7
	s_and_b32 s3, s3, 0x380
	s_lshl_b32 s4, s2, 9
	s_and_b32 s0, s0, 0x180
	v_mov_b32_e32 v12, v137
	s_or_b32 s44, s4, s0
	s_or_b32 s0, s50, s3
	v_ashrrev_i32_e32 v2, 6, v12
	v_lshlrev_b32_e32 v13, 4, v2
	s_or_b32 s0, s0, s1
	v_bfe_u32 v3, v12, 3, 3
	v_add_u32_e32 v48, s0, v13
	v_or_b32_e32 v0, v48, v3
	v_ashrrev_i32_e32 v1, 31, v0
	s_or_b32 s8, s44, s51
	v_lshlrev_b64 v[0:1], 11, v[0:1]
	v_lshl_add_u64 v[4:5], s[42:43], 0, v[0:1]
	v_add_u32_e32 v0, s8, v13
	v_or_b32_e32 v0, v0, v3
	v_ashrrev_i32_e32 v1, 31, v0
	v_and_b32_e32 v8, 63, v12
	v_lshlrev_b64 v[0:1], 11, v[0:1]
	v_lshl_add_u64 v[6:7], s[6:7], 0, v[0:1]
	v_lshlrev_b32_e32 v0, 11, v2
	v_lshlrev_b32_e32 v1, 4, v8
	v_bfe_u32 v51, v12, 4, 2
	v_add3_u32 v14, 0, v0, v1
	v_and_b32_e32 v10, 7, v12
	v_bitop3_b32 v0, v51, v12, 7 bitop3:0x78
	v_add_u32_e32 v11, 0x2000, v14
	v_lshlrev_b32_e32 v94, 4, v0
	v_readfirstlane_b32 s5, v14
	v_bitop3_b32 v10, v51, v10, 4 bitop3:0x36
	v_lshl_add_u64 v[0:1], v[4:5], 0, v[94:95]
	s_mov_b32 m0, s5
	v_lshl_add_u64 v[2:3], v[6:7], 0, v[94:95]
	v_readfirstlane_b32 s36, v11
	v_lshlrev_b32_e32 v94, 4, v10
	v_add_u32_e32 v15, 0x400, v14
	v_lshl_add_u64 v[4:5], v[4:5], 0, v[94:95]
	v_readfirstlane_b32 s37, v15
	v_add_u32_e32 v15, 0x2400, v14
	v_lshl_add_u64 v[6:7], v[6:7], 0, v[94:95]
	v_readfirstlane_b32 s38, v15
	v_add_u32_e32 v15, 0x4000, v14
	v_add_u32_e32 v16, 0x6000, v14
	v_readfirstlane_b32 s0, v15
	v_readfirstlane_b32 s1, v16
	v_add_u32_e32 v15, 0x4400, v14
	v_readfirstlane_b32 s3, v15
	v_add_u32_e32 v14, 0x6400, v14
	v_and_b32_e32 v50, 15, v12
	v_lshrrev_b32_e32 v9, 1, v12
	v_readfirstlane_b32 s4, v14
	v_or_b32_e32 v13, v13, v50
	v_bitop3_b32 v9, v51, v9, 7 bitop3:0x78
	v_lshl_add_u32 v11, v13, 7, 0
	v_lshlrev_b32_e32 v9, 4, v9
	v_add_u32_e32 v10, v11, v9
	v_bfe_u32 v12, v12, 1, 3
	v_lshl_add_u32 v13, v50, 7, 0
	v_bitop3_b32 v12, v51, v12, 4 bitop3:0x36
	v_add_u32_e32 v9, v13, v9
	v_lshlrev_b32_e32 v38, 4, v12
	v_add_u32_e32 v12, v11, v38
	v_add_u32_e32 v11, v13, v38
	s_ashr_i32 s45, s8, 6
	s_cmp_lt_i32 s45, 36
	s_mov_b64 s[0:1], -1
	v_lshrrev_b32_e32 v218, 6, v137
	v_and_b32_e32 v219, 15, v137
	v_bfe_u32 v220, v137, 4, 2
	v_bfe_u32 v221, v137, 1, 3
	v_xor_b32_e32 v220, v220, v221
	v_lshlrev_b32_e32 v220, 4, v220
	v_lshl_add_u32 v221, v218, 4, v219
	v_lshlrev_b32_e32 v222, 11, v218
	v_lshl_add_u32 v218, v221, 7, v220
	v_lshl_add_u32 v219, v219, 7, v220
	v_add_u32_e32 v219, 0x2000, v219
	v_xor_b32_e32 v220, 64, v218
	v_xor_b32_e32 v221, 64, v219
	v_readfirstlane_b32 s36, v222
	s_mov_b64 s[38:39], 0x4000
	v_lshl_add_u64 v[222:223], v[4:5], 0, s[38:39]
	v_lshl_add_u64 v[224:225], v[6:7], 0, s[38:39]
	s_mov_b64 s[38:39], 0x80
	s_waitcnt vmcnt(0) lgkmcnt(0)
	s_barrier
	s_add_i32 m0, s36, 0x0
	s_nop 0
	global_load_lds_dwordx4 v[0:1], off
	v_lshl_add_u64 v[0:1], v[0:1], 0, s[38:39]
	s_add_i32 m0, s36, 0x2000
	s_nop 0
	global_load_lds_dwordx4 v[2:3], off
	v_lshl_add_u64 v[2:3], v[2:3], 0, s[38:39]
	s_add_i32 m0, s36, 0x400
	s_nop 0
	global_load_lds_dwordx4 v[222:223], off
	v_lshl_add_u64 v[222:223], v[222:223], 0, s[38:39]
	s_add_i32 m0, s36, 0x2400
	s_nop 0
	global_load_lds_dwordx4 v[224:225], off
	v_lshl_add_u64 v[224:225], v[224:225], 0, s[38:39]
	s_add_i32 m0, s36, 0x4000
	s_nop 0
	global_load_lds_dwordx4 v[0:1], off
	v_lshl_add_u64 v[0:1], v[0:1], 0, s[38:39]
	s_add_i32 m0, s36, 0x6000
	s_nop 0
	global_load_lds_dwordx4 v[2:3], off
	v_lshl_add_u64 v[2:3], v[2:3], 0, s[38:39]
	s_add_i32 m0, s36, 0x4400
	s_nop 0
	global_load_lds_dwordx4 v[222:223], off
	v_lshl_add_u64 v[222:223], v[222:223], 0, s[38:39]
	s_add_i32 m0, s36, 0x6400
	s_nop 0
	global_load_lds_dwordx4 v[224:225], off
	v_lshl_add_u64 v[224:225], v[224:225], 0, s[38:39]
	s_add_i32 m0, s36, 0x8000
	s_nop 0
	global_load_lds_dwordx4 v[0:1], off
	v_lshl_add_u64 v[0:1], v[0:1], 0, s[38:39]
	s_add_i32 m0, s36, 0xa000
	s_nop 0
	global_load_lds_dwordx4 v[2:3], off
	v_lshl_add_u64 v[2:3], v[2:3], 0, s[38:39]
	s_add_i32 m0, s36, 0x8400
	s_nop 0
	global_load_lds_dwordx4 v[222:223], off
	v_lshl_add_u64 v[222:223], v[222:223], 0, s[38:39]
	s_add_i32 m0, s36, 0xa400
	s_nop 0
	global_load_lds_dwordx4 v[224:225], off
	v_lshl_add_u64 v[224:225], v[224:225], 0, s[38:39]
	s_waitcnt vmcnt(8)
	s_barrier
	s_add_i32 m0, s36, 0xc000
	s_nop 0
	global_load_lds_dwordx4 v[0:1], off
	v_lshl_add_u64 v[0:1], v[0:1], 0, s[38:39]
	s_add_i32 m0, s36, 0xe000
	s_nop 0
	global_load_lds_dwordx4 v[2:3], off
	v_lshl_add_u64 v[2:3], v[2:3], 0, s[38:39]
	s_add_i32 m0, s36, 0xc400
	s_nop 0
	global_load_lds_dwordx4 v[222:223], off
	v_lshl_add_u64 v[222:223], v[222:223], 0, s[38:39]
	s_add_i32 m0, s36, 0xe400
	s_nop 0
	global_load_lds_dwordx4 v[224:225], off
	v_lshl_add_u64 v[224:225], v[224:225], 0, s[38:39]
	ds_read_b128 v[138:141], v218 offset:0
	ds_read_b128 v[142:145], v220 offset:0
	ds_read_b128 v[154:157], v219 offset:0
	ds_read_b128 v[158:161], v219 offset:2048
	ds_read_b128 v[162:165], v219 offset:4096
	ds_read_b128 v[166:169], v219 offset:6144
	ds_read_b128 v[170:173], v221 offset:0
	ds_read_b128 v[174:177], v221 offset:2048
	ds_read_b128 v[178:181], v221 offset:4096
	ds_read_b128 v[182:185], v221 offset:6144
	s_waitcnt lgkmcnt(7)
	v_mfma_f32_16x16x32_bf16 v[44:47], v[138:141], v[154:157], 0
	s_waitcnt lgkmcnt(6)
	v_mfma_f32_16x16x32_bf16 v[40:43], v[138:141], v[158:161], 0
	s_waitcnt lgkmcnt(5)
	v_mfma_f32_16x16x32_bf16 v[36:39], v[138:141], v[162:165], 0
	s_waitcnt lgkmcnt(4)
	v_mfma_f32_16x16x32_bf16 v[32:35], v[138:141], v[166:169], 0
	s_waitcnt lgkmcnt(3)
	v_mfma_f32_16x16x32_bf16 v[44:47], v[142:145], v[170:173], v[44:47]
	s_waitcnt lgkmcnt(2)
	v_mfma_f32_16x16x32_bf16 v[40:43], v[142:145], v[174:177], v[40:43]
	s_waitcnt lgkmcnt(1)
	v_mfma_f32_16x16x32_bf16 v[36:39], v[142:145], v[178:181], v[36:39]
	s_waitcnt lgkmcnt(0)
	v_mfma_f32_16x16x32_bf16 v[32:35], v[142:145], v[182:185], v[32:35]
	s_waitcnt vmcnt(8)
	s_barrier
	s_add_i32 m0, s36, 0x0
	s_nop 0
	global_load_lds_dwordx4 v[0:1], off
	v_lshl_add_u64 v[0:1], v[0:1], 0, s[38:39]
	s_add_i32 m0, s36, 0x2000
	s_nop 0
	global_load_lds_dwordx4 v[2:3], off
	v_lshl_add_u64 v[2:3], v[2:3], 0, s[38:39]
	s_add_i32 m0, s36, 0x400
	s_nop 0
	global_load_lds_dwordx4 v[222:223], off
	v_lshl_add_u64 v[222:223], v[222:223], 0, s[38:39]
	s_add_i32 m0, s36, 0x2400
	s_nop 0
	global_load_lds_dwordx4 v[224:225], off
	v_lshl_add_u64 v[224:225], v[224:225], 0, s[38:39]
	ds_read_b128 v[146:149], v218 offset:16384
	ds_read_b128 v[150:153], v220 offset:16384
	ds_read_b128 v[186:189], v219 offset:16384
	ds_read_b128 v[190:193], v219 offset:18432
	ds_read_b128 v[194:197], v219 offset:20480
	ds_read_b128 v[198:201], v219 offset:22528
	ds_read_b128 v[202:205], v221 offset:16384
	ds_read_b128 v[206:209], v221 offset:18432
	ds_read_b128 v[210:213], v221 offset:20480
	ds_read_b128 v[214:217], v221 offset:22528
	s_waitcnt lgkmcnt(7)
	v_mfma_f32_16x16x32_bf16 v[44:47], v[146:149], v[186:189], v[44:47]
	s_waitcnt lgkmcnt(6)
	v_mfma_f32_16x16x32_bf16 v[40:43], v[146:149], v[190:193], v[40:43]
	s_waitcnt lgkmcnt(5)
	v_mfma_f32_16x16x32_bf16 v[36:39], v[146:149], v[194:197], v[36:39]
	s_waitcnt lgkmcnt(4)
	v_mfma_f32_16x16x32_bf16 v[32:35], v[146:149], v[198:201], v[32:35]
	s_waitcnt lgkmcnt(3)
	v_mfma_f32_16x16x32_bf16 v[44:47], v[150:153], v[202:205], v[44:47]
	s_waitcnt lgkmcnt(2)
	v_mfma_f32_16x16x32_bf16 v[40:43], v[150:153], v[206:209], v[40:43]
	s_waitcnt lgkmcnt(1)
	v_mfma_f32_16x16x32_bf16 v[36:39], v[150:153], v[210:213], v[36:39]
	s_waitcnt lgkmcnt(0)
	v_mfma_f32_16x16x32_bf16 v[32:35], v[150:153], v[214:217], v[32:35]
	s_waitcnt vmcnt(8)
	s_barrier
	s_add_i32 m0, s36, 0x4000
	s_nop 0
	global_load_lds_dwordx4 v[0:1], off
	v_lshl_add_u64 v[0:1], v[0:1], 0, s[38:39]
	s_add_i32 m0, s36, 0x6000
	s_nop 0
	global_load_lds_dwordx4 v[2:3], off
	v_lshl_add_u64 v[2:3], v[2:3], 0, s[38:39]
	s_add_i32 m0, s36, 0x4400
	s_nop 0
	global_load_lds_dwordx4 v[222:223], off
	v_lshl_add_u64 v[222:223], v[222:223], 0, s[38:39]
	s_add_i32 m0, s36, 0x6400
	s_nop 0
	global_load_lds_dwordx4 v[224:225], off
	v_lshl_add_u64 v[224:225], v[224:225], 0, s[38:39]
	ds_read_b128 v[138:141], v218 offset:32768
	ds_read_b128 v[142:145], v220 offset:32768
	ds_read_b128 v[154:157], v219 offset:32768
	ds_read_b128 v[158:161], v219 offset:34816
	ds_read_b128 v[162:165], v219 offset:36864
	ds_read_b128 v[166:169], v219 offset:38912
	ds_read_b128 v[170:173], v221 offset:32768
	ds_read_b128 v[174:177], v221 offset:34816
	ds_read_b128 v[178:181], v221 offset:36864
	ds_read_b128 v[182:185], v221 offset:38912
	s_waitcnt lgkmcnt(7)
	v_mfma_f32_16x16x32_bf16 v[44:47], v[138:141], v[154:157], v[44:47]
	s_waitcnt lgkmcnt(6)
	v_mfma_f32_16x16x32_bf16 v[40:43], v[138:141], v[158:161], v[40:43]
	s_waitcnt lgkmcnt(5)
	v_mfma_f32_16x16x32_bf16 v[36:39], v[138:141], v[162:165], v[36:39]
	s_waitcnt lgkmcnt(4)
	v_mfma_f32_16x16x32_bf16 v[32:35], v[138:141], v[166:169], v[32:35]
	s_waitcnt lgkmcnt(3)
	v_mfma_f32_16x16x32_bf16 v[44:47], v[142:145], v[170:173], v[44:47]
	s_waitcnt lgkmcnt(2)
	v_mfma_f32_16x16x32_bf16 v[40:43], v[142:145], v[174:177], v[40:43]
	s_waitcnt lgkmcnt(1)
	v_mfma_f32_16x16x32_bf16 v[36:39], v[142:145], v[178:181], v[36:39]
	s_waitcnt lgkmcnt(0)
	v_mfma_f32_16x16x32_bf16 v[32:35], v[142:145], v[182:185], v[32:35]
	s_waitcnt vmcnt(8)
	s_barrier
	s_add_i32 m0, s36, 0x8000
	s_nop 0
	global_load_lds_dwordx4 v[0:1], off
	v_lshl_add_u64 v[0:1], v[0:1], 0, s[38:39]
	s_add_i32 m0, s36, 0xa000
	s_nop 0
	global_load_lds_dwordx4 v[2:3], off
	v_lshl_add_u64 v[2:3], v[2:3], 0, s[38:39]
	s_add_i32 m0, s36, 0x8400
	s_nop 0
	global_load_lds_dwordx4 v[222:223], off
	v_lshl_add_u64 v[222:223], v[222:223], 0, s[38:39]
	s_add_i32 m0, s36, 0xa400
	s_nop 0
	global_load_lds_dwordx4 v[224:225], off
	v_lshl_add_u64 v[224:225], v[224:225], 0, s[38:39]
	ds_read_b128 v[146:149], v218 offset:49152
	ds_read_b128 v[150:153], v220 offset:49152
	ds_read_b128 v[186:189], v219 offset:49152
	ds_read_b128 v[190:193], v219 offset:51200
	ds_read_b128 v[194:197], v219 offset:53248
	ds_read_b128 v[198:201], v219 offset:55296
	ds_read_b128 v[202:205], v221 offset:49152
	ds_read_b128 v[206:209], v221 offset:51200
	ds_read_b128 v[210:213], v221 offset:53248
	ds_read_b128 v[214:217], v221 offset:55296
	s_waitcnt lgkmcnt(7)
	v_mfma_f32_16x16x32_bf16 v[44:47], v[146:149], v[186:189], v[44:47]
	s_waitcnt lgkmcnt(6)
	v_mfma_f32_16x16x32_bf16 v[40:43], v[146:149], v[190:193], v[40:43]
	s_waitcnt lgkmcnt(5)
	v_mfma_f32_16x16x32_bf16 v[36:39], v[146:149], v[194:197], v[36:39]
	s_waitcnt lgkmcnt(4)
	v_mfma_f32_16x16x32_bf16 v[32:35], v[146:149], v[198:201], v[32:35]
	s_waitcnt lgkmcnt(3)
	v_mfma_f32_16x16x32_bf16 v[44:47], v[150:153], v[202:205], v[44:47]
	s_waitcnt lgkmcnt(2)
	v_mfma_f32_16x16x32_bf16 v[40:43], v[150:153], v[206:209], v[40:43]
	s_waitcnt lgkmcnt(1)
	v_mfma_f32_16x16x32_bf16 v[36:39], v[150:153], v[210:213], v[36:39]
	s_waitcnt lgkmcnt(0)
	v_mfma_f32_16x16x32_bf16 v[32:35], v[150:153], v[214:217], v[32:35]
	s_waitcnt vmcnt(8)
	s_barrier
	s_add_i32 m0, s36, 0xc000
	s_nop 0
	global_load_lds_dwordx4 v[0:1], off
	v_lshl_add_u64 v[0:1], v[0:1], 0, s[38:39]
	s_add_i32 m0, s36, 0xe000
	s_nop 0
	global_load_lds_dwordx4 v[2:3], off
	v_lshl_add_u64 v[2:3], v[2:3], 0, s[38:39]
	s_add_i32 m0, s36, 0xc400
	s_nop 0
	global_load_lds_dwordx4 v[222:223], off
	v_lshl_add_u64 v[222:223], v[222:223], 0, s[38:39]
	s_add_i32 m0, s36, 0xe400
	s_nop 0
	global_load_lds_dwordx4 v[224:225], off
	v_lshl_add_u64 v[224:225], v[224:225], 0, s[38:39]
	ds_read_b128 v[138:141], v218 offset:0
	ds_read_b128 v[142:145], v220 offset:0
	ds_read_b128 v[154:157], v219 offset:0
	ds_read_b128 v[158:161], v219 offset:2048
	ds_read_b128 v[162:165], v219 offset:4096
	ds_read_b128 v[166:169], v219 offset:6144
	ds_read_b128 v[170:173], v221 offset:0
	ds_read_b128 v[174:177], v221 offset:2048
	ds_read_b128 v[178:181], v221 offset:4096
	ds_read_b128 v[182:185], v221 offset:6144
	s_waitcnt lgkmcnt(7)
	v_mfma_f32_16x16x32_bf16 v[44:47], v[138:141], v[154:157], v[44:47]
	s_waitcnt lgkmcnt(6)
	v_mfma_f32_16x16x32_bf16 v[40:43], v[138:141], v[158:161], v[40:43]
	s_waitcnt lgkmcnt(5)
	v_mfma_f32_16x16x32_bf16 v[36:39], v[138:141], v[162:165], v[36:39]
	s_waitcnt lgkmcnt(4)
	v_mfma_f32_16x16x32_bf16 v[32:35], v[138:141], v[166:169], v[32:35]
	s_waitcnt lgkmcnt(3)
	v_mfma_f32_16x16x32_bf16 v[44:47], v[142:145], v[170:173], v[44:47]
	s_waitcnt lgkmcnt(2)
	v_mfma_f32_16x16x32_bf16 v[40:43], v[142:145], v[174:177], v[40:43]
	s_waitcnt lgkmcnt(1)
	v_mfma_f32_16x16x32_bf16 v[36:39], v[142:145], v[178:181], v[36:39]
	s_waitcnt lgkmcnt(0)
	v_mfma_f32_16x16x32_bf16 v[32:35], v[142:145], v[182:185], v[32:35]
	s_waitcnt vmcnt(8)
	s_barrier
	s_add_i32 m0, s36, 0x0
	s_nop 0
	global_load_lds_dwordx4 v[0:1], off
	v_lshl_add_u64 v[0:1], v[0:1], 0, s[38:39]
	s_add_i32 m0, s36, 0x2000
	s_nop 0
	global_load_lds_dwordx4 v[2:3], off
	v_lshl_add_u64 v[2:3], v[2:3], 0, s[38:39]
	s_add_i32 m0, s36, 0x400
	s_nop 0
	global_load_lds_dwordx4 v[222:223], off
	v_lshl_add_u64 v[222:223], v[222:223], 0, s[38:39]
	s_add_i32 m0, s36, 0x2400
	s_nop 0
	global_load_lds_dwordx4 v[224:225], off
	v_lshl_add_u64 v[224:225], v[224:225], 0, s[38:39]
	ds_read_b128 v[146:149], v218 offset:16384
	ds_read_b128 v[150:153], v220 offset:16384
	ds_read_b128 v[186:189], v219 offset:16384
	ds_read_b128 v[190:193], v219 offset:18432
	ds_read_b128 v[194:197], v219 offset:20480
	ds_read_b128 v[198:201], v219 offset:22528
	ds_read_b128 v[202:205], v221 offset:16384
	ds_read_b128 v[206:209], v221 offset:18432
	ds_read_b128 v[210:213], v221 offset:20480
	ds_read_b128 v[214:217], v221 offset:22528
	s_waitcnt lgkmcnt(7)
	v_mfma_f32_16x16x32_bf16 v[44:47], v[146:149], v[186:189], v[44:47]
	s_waitcnt lgkmcnt(6)
	v_mfma_f32_16x16x32_bf16 v[40:43], v[146:149], v[190:193], v[40:43]
	s_waitcnt lgkmcnt(5)
	v_mfma_f32_16x16x32_bf16 v[36:39], v[146:149], v[194:197], v[36:39]
	s_waitcnt lgkmcnt(4)
	v_mfma_f32_16x16x32_bf16 v[32:35], v[146:149], v[198:201], v[32:35]
	s_waitcnt lgkmcnt(3)
	v_mfma_f32_16x16x32_bf16 v[44:47], v[150:153], v[202:205], v[44:47]
	s_waitcnt lgkmcnt(2)
	v_mfma_f32_16x16x32_bf16 v[40:43], v[150:153], v[206:209], v[40:43]
	s_waitcnt lgkmcnt(1)
	v_mfma_f32_16x16x32_bf16 v[36:39], v[150:153], v[210:213], v[36:39]
	s_waitcnt lgkmcnt(0)
	v_mfma_f32_16x16x32_bf16 v[32:35], v[150:153], v[214:217], v[32:35]
	s_waitcnt vmcnt(8)
	s_barrier
	s_add_i32 m0, s36, 0x4000
	s_nop 0
	global_load_lds_dwordx4 v[0:1], off
	v_lshl_add_u64 v[0:1], v[0:1], 0, s[38:39]
	s_add_i32 m0, s36, 0x6000
	s_nop 0
	global_load_lds_dwordx4 v[2:3], off
	v_lshl_add_u64 v[2:3], v[2:3], 0, s[38:39]
	s_add_i32 m0, s36, 0x4400
	s_nop 0
	global_load_lds_dwordx4 v[222:223], off
	v_lshl_add_u64 v[222:223], v[222:223], 0, s[38:39]
	s_add_i32 m0, s36, 0x6400
	s_nop 0
	global_load_lds_dwordx4 v[224:225], off
	v_lshl_add_u64 v[224:225], v[224:225], 0, s[38:39]
	ds_read_b128 v[138:141], v218 offset:32768
	ds_read_b128 v[142:145], v220 offset:32768
	ds_read_b128 v[154:157], v219 offset:32768
	ds_read_b128 v[158:161], v219 offset:34816
	ds_read_b128 v[162:165], v219 offset:36864
	ds_read_b128 v[166:169], v219 offset:38912
	ds_read_b128 v[170:173], v221 offset:32768
	ds_read_b128 v[174:177], v221 offset:34816
	ds_read_b128 v[178:181], v221 offset:36864
	ds_read_b128 v[182:185], v221 offset:38912
	s_waitcnt lgkmcnt(7)
	v_mfma_f32_16x16x32_bf16 v[44:47], v[138:141], v[154:157], v[44:47]
	s_waitcnt lgkmcnt(6)
	v_mfma_f32_16x16x32_bf16 v[40:43], v[138:141], v[158:161], v[40:43]
	s_waitcnt lgkmcnt(5)
	v_mfma_f32_16x16x32_bf16 v[36:39], v[138:141], v[162:165], v[36:39]
	s_waitcnt lgkmcnt(4)
	v_mfma_f32_16x16x32_bf16 v[32:35], v[138:141], v[166:169], v[32:35]
	s_waitcnt lgkmcnt(3)
	v_mfma_f32_16x16x32_bf16 v[44:47], v[142:145], v[170:173], v[44:47]
	s_waitcnt lgkmcnt(2)
	v_mfma_f32_16x16x32_bf16 v[40:43], v[142:145], v[174:177], v[40:43]
	s_waitcnt lgkmcnt(1)
	v_mfma_f32_16x16x32_bf16 v[36:39], v[142:145], v[178:181], v[36:39]
	s_waitcnt lgkmcnt(0)
	v_mfma_f32_16x16x32_bf16 v[32:35], v[142:145], v[182:185], v[32:35]
	s_waitcnt vmcnt(8)
	s_barrier
	s_add_i32 m0, s36, 0x8000
	s_nop 0
	global_load_lds_dwordx4 v[0:1], off
	v_lshl_add_u64 v[0:1], v[0:1], 0, s[38:39]
	s_add_i32 m0, s36, 0xa000
	s_nop 0
	global_load_lds_dwordx4 v[2:3], off
	v_lshl_add_u64 v[2:3], v[2:3], 0, s[38:39]
	s_add_i32 m0, s36, 0x8400
	s_nop 0
	global_load_lds_dwordx4 v[222:223], off
	v_lshl_add_u64 v[222:223], v[222:223], 0, s[38:39]
	s_add_i32 m0, s36, 0xa400
	s_nop 0
	global_load_lds_dwordx4 v[224:225], off
	v_lshl_add_u64 v[224:225], v[224:225], 0, s[38:39]
	ds_read_b128 v[146:149], v218 offset:49152
	ds_read_b128 v[150:153], v220 offset:49152
	ds_read_b128 v[186:189], v219 offset:49152
	ds_read_b128 v[190:193], v219 offset:51200
	ds_read_b128 v[194:197], v219 offset:53248
	ds_read_b128 v[198:201], v219 offset:55296
	ds_read_b128 v[202:205], v221 offset:49152
	ds_read_b128 v[206:209], v221 offset:51200
	ds_read_b128 v[210:213], v221 offset:53248
	ds_read_b128 v[214:217], v221 offset:55296
	s_waitcnt lgkmcnt(7)
	v_mfma_f32_16x16x32_bf16 v[44:47], v[146:149], v[186:189], v[44:47]
	s_waitcnt lgkmcnt(6)
	v_mfma_f32_16x16x32_bf16 v[40:43], v[146:149], v[190:193], v[40:43]
	s_waitcnt lgkmcnt(5)
	v_mfma_f32_16x16x32_bf16 v[36:39], v[146:149], v[194:197], v[36:39]
	s_waitcnt lgkmcnt(4)
	v_mfma_f32_16x16x32_bf16 v[32:35], v[146:149], v[198:201], v[32:35]
	s_waitcnt lgkmcnt(3)
	v_mfma_f32_16x16x32_bf16 v[44:47], v[150:153], v[202:205], v[44:47]
	s_waitcnt lgkmcnt(2)
	v_mfma_f32_16x16x32_bf16 v[40:43], v[150:153], v[206:209], v[40:43]
	s_waitcnt lgkmcnt(1)
	v_mfma_f32_16x16x32_bf16 v[36:39], v[150:153], v[210:213], v[36:39]
	s_waitcnt lgkmcnt(0)
	v_mfma_f32_16x16x32_bf16 v[32:35], v[150:153], v[214:217], v[32:35]
	s_waitcnt vmcnt(8)
	s_barrier
	s_add_i32 m0, s36, 0xc000
	s_nop 0
	global_load_lds_dwordx4 v[0:1], off
	v_lshl_add_u64 v[0:1], v[0:1], 0, s[38:39]
	s_add_i32 m0, s36, 0xe000
	s_nop 0
	global_load_lds_dwordx4 v[2:3], off
	v_lshl_add_u64 v[2:3], v[2:3], 0, s[38:39]
	s_add_i32 m0, s36, 0xc400
	s_nop 0
	global_load_lds_dwordx4 v[222:223], off
	v_lshl_add_u64 v[222:223], v[222:223], 0, s[38:39]
	s_add_i32 m0, s36, 0xe400
	s_nop 0
	global_load_lds_dwordx4 v[224:225], off
	v_lshl_add_u64 v[224:225], v[224:225], 0, s[38:39]
	ds_read_b128 v[138:141], v218 offset:0
	ds_read_b128 v[142:145], v220 offset:0
	ds_read_b128 v[154:157], v219 offset:0
	ds_read_b128 v[158:161], v219 offset:2048
	ds_read_b128 v[162:165], v219 offset:4096
	ds_read_b128 v[166:169], v219 offset:6144
	ds_read_b128 v[170:173], v221 offset:0
	ds_read_b128 v[174:177], v221 offset:2048
	ds_read_b128 v[178:181], v221 offset:4096
	ds_read_b128 v[182:185], v221 offset:6144
	s_waitcnt lgkmcnt(7)
	v_mfma_f32_16x16x32_bf16 v[44:47], v[138:141], v[154:157], v[44:47]
	s_waitcnt lgkmcnt(6)
	v_mfma_f32_16x16x32_bf16 v[40:43], v[138:141], v[158:161], v[40:43]
	s_waitcnt lgkmcnt(5)
	v_mfma_f32_16x16x32_bf16 v[36:39], v[138:141], v[162:165], v[36:39]
	s_waitcnt lgkmcnt(4)
	v_mfma_f32_16x16x32_bf16 v[32:35], v[138:141], v[166:169], v[32:35]
	s_waitcnt lgkmcnt(3)
	v_mfma_f32_16x16x32_bf16 v[44:47], v[142:145], v[170:173], v[44:47]
	s_waitcnt lgkmcnt(2)
	v_mfma_f32_16x16x32_bf16 v[40:43], v[142:145], v[174:177], v[40:43]
	s_waitcnt lgkmcnt(1)
	v_mfma_f32_16x16x32_bf16 v[36:39], v[142:145], v[178:181], v[36:39]
	s_waitcnt lgkmcnt(0)
	v_mfma_f32_16x16x32_bf16 v[32:35], v[142:145], v[182:185], v[32:35]
	s_waitcnt vmcnt(8)
	s_barrier
	s_add_i32 m0, s36, 0x0
	s_nop 0
	global_load_lds_dwordx4 v[0:1], off
	v_lshl_add_u64 v[0:1], v[0:1], 0, s[38:39]
	s_add_i32 m0, s36, 0x2000
	s_nop 0
	global_load_lds_dwordx4 v[2:3], off
	v_lshl_add_u64 v[2:3], v[2:3], 0, s[38:39]
	s_add_i32 m0, s36, 0x400
	s_nop 0
	global_load_lds_dwordx4 v[222:223], off
	v_lshl_add_u64 v[222:223], v[222:223], 0, s[38:39]
	s_add_i32 m0, s36, 0x2400
	s_nop 0
	global_load_lds_dwordx4 v[224:225], off
	v_lshl_add_u64 v[224:225], v[224:225], 0, s[38:39]
	ds_read_b128 v[146:149], v218 offset:16384
	ds_read_b128 v[150:153], v220 offset:16384
	ds_read_b128 v[186:189], v219 offset:16384
	ds_read_b128 v[190:193], v219 offset:18432
	ds_read_b128 v[194:197], v219 offset:20480
	ds_read_b128 v[198:201], v219 offset:22528
	ds_read_b128 v[202:205], v221 offset:16384
	ds_read_b128 v[206:209], v221 offset:18432
	ds_read_b128 v[210:213], v221 offset:20480
	ds_read_b128 v[214:217], v221 offset:22528
	s_waitcnt lgkmcnt(7)
	v_mfma_f32_16x16x32_bf16 v[44:47], v[146:149], v[186:189], v[44:47]
	s_waitcnt lgkmcnt(6)
	v_mfma_f32_16x16x32_bf16 v[40:43], v[146:149], v[190:193], v[40:43]
	s_waitcnt lgkmcnt(5)
	v_mfma_f32_16x16x32_bf16 v[36:39], v[146:149], v[194:197], v[36:39]
	s_waitcnt lgkmcnt(4)
	v_mfma_f32_16x16x32_bf16 v[32:35], v[146:149], v[198:201], v[32:35]
	s_waitcnt lgkmcnt(3)
	v_mfma_f32_16x16x32_bf16 v[44:47], v[150:153], v[202:205], v[44:47]
	s_waitcnt lgkmcnt(2)
	v_mfma_f32_16x16x32_bf16 v[40:43], v[150:153], v[206:209], v[40:43]
	s_waitcnt lgkmcnt(1)
	v_mfma_f32_16x16x32_bf16 v[36:39], v[150:153], v[210:213], v[36:39]
	s_waitcnt lgkmcnt(0)
	v_mfma_f32_16x16x32_bf16 v[32:35], v[150:153], v[214:217], v[32:35]
	s_waitcnt vmcnt(8)
	s_barrier
	s_add_i32 m0, s36, 0x4000
	s_nop 0
	global_load_lds_dwordx4 v[0:1], off
	v_lshl_add_u64 v[0:1], v[0:1], 0, s[38:39]
	s_add_i32 m0, s36, 0x6000
	s_nop 0
	global_load_lds_dwordx4 v[2:3], off
	v_lshl_add_u64 v[2:3], v[2:3], 0, s[38:39]
	s_add_i32 m0, s36, 0x4400
	s_nop 0
	global_load_lds_dwordx4 v[222:223], off
	v_lshl_add_u64 v[222:223], v[222:223], 0, s[38:39]
	s_add_i32 m0, s36, 0x6400
	s_nop 0
	global_load_lds_dwordx4 v[224:225], off
	v_lshl_add_u64 v[224:225], v[224:225], 0, s[38:39]
	ds_read_b128 v[138:141], v218 offset:32768
	ds_read_b128 v[142:145], v220 offset:32768
	ds_read_b128 v[154:157], v219 offset:32768
	ds_read_b128 v[158:161], v219 offset:34816
	ds_read_b128 v[162:165], v219 offset:36864
	ds_read_b128 v[166:169], v219 offset:38912
	ds_read_b128 v[170:173], v221 offset:32768
	ds_read_b128 v[174:177], v221 offset:34816
	ds_read_b128 v[178:181], v221 offset:36864
	ds_read_b128 v[182:185], v221 offset:38912
	s_waitcnt lgkmcnt(7)
	v_mfma_f32_16x16x32_bf16 v[44:47], v[138:141], v[154:157], v[44:47]
	s_waitcnt lgkmcnt(6)
	v_mfma_f32_16x16x32_bf16 v[40:43], v[138:141], v[158:161], v[40:43]
	s_waitcnt lgkmcnt(5)
	v_mfma_f32_16x16x32_bf16 v[36:39], v[138:141], v[162:165], v[36:39]
	s_waitcnt lgkmcnt(4)
	v_mfma_f32_16x16x32_bf16 v[32:35], v[138:141], v[166:169], v[32:35]
	s_waitcnt lgkmcnt(3)
	v_mfma_f32_16x16x32_bf16 v[44:47], v[142:145], v[170:173], v[44:47]
	s_waitcnt lgkmcnt(2)
	v_mfma_f32_16x16x32_bf16 v[40:43], v[142:145], v[174:177], v[40:43]
	s_waitcnt lgkmcnt(1)
	v_mfma_f32_16x16x32_bf16 v[36:39], v[142:145], v[178:181], v[36:39]
	s_waitcnt lgkmcnt(0)
	v_mfma_f32_16x16x32_bf16 v[32:35], v[142:145], v[182:185], v[32:35]
	s_waitcnt vmcnt(8)
	s_barrier
	s_add_i32 m0, s36, 0x8000
	s_nop 0
	global_load_lds_dwordx4 v[0:1], off
	v_lshl_add_u64 v[0:1], v[0:1], 0, s[38:39]
	s_add_i32 m0, s36, 0xa000
	s_nop 0
	global_load_lds_dwordx4 v[2:3], off
	v_lshl_add_u64 v[2:3], v[2:3], 0, s[38:39]
	s_add_i32 m0, s36, 0x8400
	s_nop 0
	global_load_lds_dwordx4 v[222:223], off
	v_lshl_add_u64 v[222:223], v[222:223], 0, s[38:39]
	s_add_i32 m0, s36, 0xa400
	s_nop 0
	global_load_lds_dwordx4 v[224:225], off
	v_lshl_add_u64 v[224:225], v[224:225], 0, s[38:39]
	ds_read_b128 v[146:149], v218 offset:49152
	ds_read_b128 v[150:153], v220 offset:49152
	ds_read_b128 v[186:189], v219 offset:49152
	ds_read_b128 v[190:193], v219 offset:51200
	ds_read_b128 v[194:197], v219 offset:53248
	ds_read_b128 v[198:201], v219 offset:55296
	ds_read_b128 v[202:205], v221 offset:49152
	ds_read_b128 v[206:209], v221 offset:51200
	ds_read_b128 v[210:213], v221 offset:53248
	ds_read_b128 v[214:217], v221 offset:55296
	s_waitcnt lgkmcnt(7)
	v_mfma_f32_16x16x32_bf16 v[44:47], v[146:149], v[186:189], v[44:47]
	s_waitcnt lgkmcnt(6)
	v_mfma_f32_16x16x32_bf16 v[40:43], v[146:149], v[190:193], v[40:43]
	s_waitcnt lgkmcnt(5)
	v_mfma_f32_16x16x32_bf16 v[36:39], v[146:149], v[194:197], v[36:39]
	s_waitcnt lgkmcnt(4)
	v_mfma_f32_16x16x32_bf16 v[32:35], v[146:149], v[198:201], v[32:35]
	s_waitcnt lgkmcnt(3)
	v_mfma_f32_16x16x32_bf16 v[44:47], v[150:153], v[202:205], v[44:47]
	s_waitcnt lgkmcnt(2)
	v_mfma_f32_16x16x32_bf16 v[40:43], v[150:153], v[206:209], v[40:43]
	s_waitcnt lgkmcnt(1)
	v_mfma_f32_16x16x32_bf16 v[36:39], v[150:153], v[210:213], v[36:39]
	s_waitcnt lgkmcnt(0)
	v_mfma_f32_16x16x32_bf16 v[32:35], v[150:153], v[214:217], v[32:35]
	s_waitcnt vmcnt(8)
	s_barrier
	s_add_i32 m0, s36, 0xc000
	s_nop 0
	global_load_lds_dwordx4 v[0:1], off
	v_lshl_add_u64 v[0:1], v[0:1], 0, s[38:39]
	s_add_i32 m0, s36, 0xe000
	s_nop 0
	global_load_lds_dwordx4 v[2:3], off
	v_lshl_add_u64 v[2:3], v[2:3], 0, s[38:39]
	s_add_i32 m0, s36, 0xc400
	s_nop 0
	global_load_lds_dwordx4 v[222:223], off
	v_lshl_add_u64 v[222:223], v[222:223], 0, s[38:39]
	s_add_i32 m0, s36, 0xe400
	s_nop 0
	global_load_lds_dwordx4 v[224:225], off
	v_lshl_add_u64 v[224:225], v[224:225], 0, s[38:39]
	ds_read_b128 v[138:141], v218 offset:0
	ds_read_b128 v[142:145], v220 offset:0
	ds_read_b128 v[154:157], v219 offset:0
	ds_read_b128 v[158:161], v219 offset:2048
	ds_read_b128 v[162:165], v219 offset:4096
	ds_read_b128 v[166:169], v219 offset:6144
	ds_read_b128 v[170:173], v221 offset:0
	ds_read_b128 v[174:177], v221 offset:2048
	ds_read_b128 v[178:181], v221 offset:4096
	ds_read_b128 v[182:185], v221 offset:6144
	s_waitcnt lgkmcnt(7)
	v_mfma_f32_16x16x32_bf16 v[44:47], v[138:141], v[154:157], v[44:47]
	s_waitcnt lgkmcnt(6)
	v_mfma_f32_16x16x32_bf16 v[40:43], v[138:141], v[158:161], v[40:43]
	s_waitcnt lgkmcnt(5)
	v_mfma_f32_16x16x32_bf16 v[36:39], v[138:141], v[162:165], v[36:39]
	s_waitcnt lgkmcnt(4)
	v_mfma_f32_16x16x32_bf16 v[32:35], v[138:141], v[166:169], v[32:35]
	s_waitcnt lgkmcnt(3)
	v_mfma_f32_16x16x32_bf16 v[44:47], v[142:145], v[170:173], v[44:47]
	s_waitcnt lgkmcnt(2)
	v_mfma_f32_16x16x32_bf16 v[40:43], v[142:145], v[174:177], v[40:43]
	s_waitcnt lgkmcnt(1)
	v_mfma_f32_16x16x32_bf16 v[36:39], v[142:145], v[178:181], v[36:39]
	s_waitcnt lgkmcnt(0)
	v_mfma_f32_16x16x32_bf16 v[32:35], v[142:145], v[182:185], v[32:35]
	s_waitcnt vmcnt(8)
	s_barrier
	ds_read_b128 v[146:149], v218 offset:16384
	ds_read_b128 v[150:153], v220 offset:16384
	ds_read_b128 v[186:189], v219 offset:16384
	ds_read_b128 v[190:193], v219 offset:18432
	ds_read_b128 v[194:197], v219 offset:20480
	ds_read_b128 v[198:201], v219 offset:22528
	ds_read_b128 v[202:205], v221 offset:16384
	ds_read_b128 v[206:209], v221 offset:18432
	ds_read_b128 v[210:213], v221 offset:20480
	ds_read_b128 v[214:217], v221 offset:22528
	s_waitcnt lgkmcnt(7)
	v_mfma_f32_16x16x32_bf16 v[44:47], v[146:149], v[186:189], v[44:47]
	s_waitcnt lgkmcnt(6)
	v_mfma_f32_16x16x32_bf16 v[40:43], v[146:149], v[190:193], v[40:43]
	s_waitcnt lgkmcnt(5)
	v_mfma_f32_16x16x32_bf16 v[36:39], v[146:149], v[194:197], v[36:39]
	s_waitcnt lgkmcnt(4)
	v_mfma_f32_16x16x32_bf16 v[32:35], v[146:149], v[198:201], v[32:35]
	s_waitcnt lgkmcnt(3)
	v_mfma_f32_16x16x32_bf16 v[44:47], v[150:153], v[202:205], v[44:47]
	s_waitcnt lgkmcnt(2)
	v_mfma_f32_16x16x32_bf16 v[40:43], v[150:153], v[206:209], v[40:43]
	s_waitcnt lgkmcnt(1)
	v_mfma_f32_16x16x32_bf16 v[36:39], v[150:153], v[210:213], v[36:39]
	s_waitcnt lgkmcnt(0)
	v_mfma_f32_16x16x32_bf16 v[32:35], v[150:153], v[214:217], v[32:35]
	s_waitcnt vmcnt(4)
	s_barrier
	ds_read_b128 v[138:141], v218 offset:32768
	ds_read_b128 v[142:145], v220 offset:32768
	ds_read_b128 v[154:157], v219 offset:32768
	ds_read_b128 v[158:161], v219 offset:34816
	ds_read_b128 v[162:165], v219 offset:36864
	ds_read_b128 v[166:169], v219 offset:38912
	ds_read_b128 v[170:173], v221 offset:32768
	ds_read_b128 v[174:177], v221 offset:34816
	ds_read_b128 v[178:181], v221 offset:36864
	ds_read_b128 v[182:185], v221 offset:38912
	s_waitcnt lgkmcnt(7)
	v_mfma_f32_16x16x32_bf16 v[44:47], v[138:141], v[154:157], v[44:47]
	s_waitcnt lgkmcnt(6)
	v_mfma_f32_16x16x32_bf16 v[40:43], v[138:141], v[158:161], v[40:43]
	s_waitcnt lgkmcnt(5)
	v_mfma_f32_16x16x32_bf16 v[36:39], v[138:141], v[162:165], v[36:39]
	s_waitcnt lgkmcnt(4)
	v_mfma_f32_16x16x32_bf16 v[32:35], v[138:141], v[166:169], v[32:35]
	s_waitcnt lgkmcnt(3)
	v_mfma_f32_16x16x32_bf16 v[44:47], v[142:145], v[170:173], v[44:47]
	s_waitcnt lgkmcnt(2)
	v_mfma_f32_16x16x32_bf16 v[40:43], v[142:145], v[174:177], v[40:43]
	s_waitcnt lgkmcnt(1)
	v_mfma_f32_16x16x32_bf16 v[36:39], v[142:145], v[178:181], v[36:39]
	s_waitcnt lgkmcnt(0)
	v_mfma_f32_16x16x32_bf16 v[32:35], v[142:145], v[182:185], v[32:35]
	s_waitcnt vmcnt(0)
	s_barrier
	ds_read_b128 v[146:149], v218 offset:49152
	ds_read_b128 v[150:153], v220 offset:49152
	ds_read_b128 v[186:189], v219 offset:49152
	ds_read_b128 v[190:193], v219 offset:51200
	ds_read_b128 v[194:197], v219 offset:53248
	ds_read_b128 v[198:201], v219 offset:55296
	ds_read_b128 v[202:205], v221 offset:49152
	ds_read_b128 v[206:209], v221 offset:51200
	ds_read_b128 v[210:213], v221 offset:53248
	ds_read_b128 v[214:217], v221 offset:55296
	s_waitcnt lgkmcnt(7)
	v_mfma_f32_16x16x32_bf16 v[44:47], v[146:149], v[186:189], v[44:47]
	s_waitcnt lgkmcnt(6)
	v_mfma_f32_16x16x32_bf16 v[40:43], v[146:149], v[190:193], v[40:43]
	s_waitcnt lgkmcnt(5)
	v_mfma_f32_16x16x32_bf16 v[36:39], v[146:149], v[194:197], v[36:39]
	s_waitcnt lgkmcnt(4)
	v_mfma_f32_16x16x32_bf16 v[32:35], v[146:149], v[198:201], v[32:35]
	s_waitcnt lgkmcnt(3)
	v_mfma_f32_16x16x32_bf16 v[44:47], v[150:153], v[202:205], v[44:47]
	s_waitcnt lgkmcnt(2)
	v_mfma_f32_16x16x32_bf16 v[40:43], v[150:153], v[206:209], v[40:43]
	s_waitcnt lgkmcnt(1)
	v_mfma_f32_16x16x32_bf16 v[36:39], v[150:153], v[210:213], v[36:39]
	s_waitcnt lgkmcnt(0)
	v_mfma_f32_16x16x32_bf16 v[32:35], v[150:153], v[214:217], v[32:35]
	s_nop 7
	s_nop 1
	s_cmp_lt_i32 s45, 36
	s_cbranch_scc0 .LBB0_1417
	s_cmp_lt_i32 s45, 18
	s_cbranch_scc0 .LBB0_1414
	s_cmp_lg_u32 s2, 1
	s_cbranch_scc1 .LBB0_1385
	v_readlane_b32 s12, v242, 10
	s_cmp_lt_i32 s45, 14
	v_readlane_b32 s16, v242, 14
	v_readlane_b32 s17, v242, 15
	v_readlane_b32 s18, v242, 16
	v_readlane_b32 s19, v242, 17
	s_cselect_b32 s1, s17, s19
	s_cselect_b32 s0, s16, s18
	v_lshlrev_b32_e32 v0, 2, v50
	global_load_dword v2, v0, s[0:1] offset:256
	global_load_dword v6, v0, s[0:1] offset:320
	global_load_dword v10, v0, s[0:1] offset:384
	v_lshl_or_b32 v0, v8, 2, v129
	global_load_dword v14, v0, s[0:1] offset:256
	v_mov_b32_e32 v0, v44
	v_mov_b32_e32 v1, v40
	v_pk_mul_f32 v[0:1], v[0:1], v[0:1]
	v_mov_b32_e32 v4, v36
	v_mov_b32_e32 v5, v32
	v_pk_mul_f32 v[4:5], v[4:5], v[4:5]
	v_add_f32_e32 v0, v0, v1
	v_add_f32_e32 v0, v4, v0
	v_add_f32_e32 v0, v0, v5
	v_mov_b32_e32 v1, v41
	v_mov_b32_e32 v4, v37
	v_add_f32_dpp v0, v0, v0 quad_perm:[1,0,3,2] row_mask:0xf bank_mask:0xf bound_ctrl:1
	v_mov_b32_e32 v5, v33
	v_pk_mul_f32 v[4:5], v[4:5], v[4:5]
	v_add_f32_dpp v0, v0, v0 quad_perm:[2,3,0,1] row_mask:0xf bank_mask:0xf bound_ctrl:1
	v_mov_b32_e32 v16, v46
	v_mov_b32_e32 v17, v42
	v_add_f32_dpp v0, v0, v0 row_ror:4 row_mask:0xf bank_mask:0xf bound_ctrl:1
	v_pk_mul_f32 v[16:17], v[16:17], v[16:17]
	v_mov_b32_e32 v18, v38
	v_add_f32_dpp v0, v0, v0 row_ror:8 row_mask:0xf bank_mask:0xf bound_ctrl:1
	v_fmamk_f32 v0, v0, 0x3c800000, v124
	v_rsq_f32_e32 v12, v0
	v_mov_b32_e32 v0, v45
	v_pk_mul_f32 v[0:1], v[0:1], v[0:1]
	v_mov_b32_e32 v19, v34
	v_add_f32_e32 v0, v0, v1
	v_add_f32_e32 v0, v4, v0
	v_add_f32_e32 v0, v0, v5
	v_pk_mul_f32 v[18:19], v[18:19], v[18:19]
	v_mov_b32_e32 v20, v39
	v_add_f32_dpp v0, v0, v0 quad_perm:[1,0,3,2] row_mask:0xf bank_mask:0xf bound_ctrl:1
	v_mov_b32_e32 v21, v35
	v_pk_mul_f32 v[20:21], v[20:21], v[20:21]
	v_add_f32_dpp v0, v0, v0 quad_perm:[2,3,0,1] row_mask:0xf bank_mask:0xf bound_ctrl:1
	v_readlane_b32 s20, v242, 18
	v_readlane_b32 s21, v242, 19
	v_add_f32_dpp v0, v0, v0 row_ror:4 row_mask:0xf bank_mask:0xf bound_ctrl:1
	v_readlane_b32 s22, v242, 20
	v_readlane_b32 s23, v242, 21
	v_add_f32_dpp v0, v0, v0 row_ror:8 row_mask:0xf bank_mask:0xf bound_ctrl:1
	v_fmamk_f32 v0, v0, 0x3c800000, v124
	v_rsq_f32_e32 v13, v0
	v_readlane_b32 s24, v242, 22
	v_readlane_b32 s25, v242, 23
	v_readlane_b32 s26, v242, 24
	v_readlane_b32 s27, v242, 25
	s_mov_b64 s[26:27], 0x200
	s_mov_b64 s[22:23], 0x180
	s_mov_b64 s[24:25], 0x4180
	s_mov_b64 s[20:21], 0x4100
	s_mov_b64 s[18:19], 0x100
	s_mov_b64 s[16:17], 0x4080
	v_readlane_b32 s13, v242, 11
	v_readlane_b32 s14, v242, 12
	v_readlane_b32 s15, v242, 13
	s_waitcnt vmcnt(3)
	v_pk_mul_f32 v[0:1], v[2:3], v[12:13] op_sel_hi:[0,1]
	v_add_f32_e32 v3, v16, v17
	v_add_f32_e32 v3, v18, v3
	v_add_f32_e32 v3, v3, v19
	v_mov_b32_e32 v18, v47
	v_mov_b32_e32 v19, v43
	v_add_f32_dpp v3, v3, v3 quad_perm:[1,0,3,2] row_mask:0xf bank_mask:0xf bound_ctrl:1
	v_pk_mul_f32 v[18:19], v[18:19], v[18:19]
	s_waitcnt vmcnt(2)
	v_pk_mul_f32 v[4:5], v[6:7], v[12:13] op_sel_hi:[0,1]
	v_add_f32_dpp v3, v3, v3 quad_perm:[2,3,0,1] row_mask:0xf bank_mask:0xf bound_ctrl:1
	s_waitcnt vmcnt(1)
	v_pk_mul_f32 v[8:9], v[10:11], v[12:13] op_sel_hi:[0,1]
	s_waitcnt vmcnt(0)
	v_pk_mul_f32 v[12:13], v[14:15], v[12:13] op_sel_hi:[0,1]
	v_add_f32_dpp v3, v3, v3 row_ror:4 row_mask:0xf bank_mask:0xf bound_ctrl:1
	v_pk_mul_f32 v[0:1], v[44:45], v[0:1]
	v_pk_mul_f32 v[4:5], v[40:41], v[4:5]
	v_add_f32_dpp v3, v3, v3 row_ror:8 row_mask:0xf bank_mask:0xf bound_ctrl:1
	v_fmamk_f32 v3, v3, 0x3c800000, v124
	v_rsq_f32_e32 v16, v3
	v_add_f32_e32 v3, v18, v19
	v_add_f32_e32 v3, v20, v3
	v_add_f32_e32 v3, v3, v21
	v_pk_mul_f32 v[8:9], v[36:37], v[8:9]
	v_pk_mul_f32 v[12:13], v[32:33], v[12:13]
	v_add_f32_dpp v3, v3, v3 quad_perm:[1,0,3,2] row_mask:0xf bank_mask:0xf bound_ctrl:1
	s_nop 1
	v_add_f32_dpp v3, v3, v3 quad_perm:[2,3,0,1] row_mask:0xf bank_mask:0xf bound_ctrl:1
	s_nop 1
	v_add_f32_dpp v3, v3, v3 row_ror:4 row_mask:0xf bank_mask:0xf bound_ctrl:1
	s_nop 1
	v_add_f32_dpp v3, v3, v3 row_ror:8 row_mask:0xf bank_mask:0xf bound_ctrl:1
	v_fmamk_f32 v3, v3, 0x3c800000, v124
	v_rsq_f32_e32 v17, v3
	s_nop 0
	v_pk_mul_f32 v[2:3], v[2:3], v[16:17] op_sel_hi:[0,1]
	v_pk_mul_f32 v[6:7], v[6:7], v[16:17] op_sel_hi:[0,1]
	v_pk_mul_f32 v[10:11], v[10:11], v[16:17] op_sel_hi:[0,1]
	v_pk_mul_f32 v[14:15], v[14:15], v[16:17] op_sel_hi:[0,1]
	v_pk_mul_f32 v[2:3], v[46:47], v[2:3]
	v_pk_mul_f32 v[6:7], v[42:43], v[6:7]
	v_pk_mul_f32 v[10:11], v[38:39], v[10:11]
	v_pk_mul_f32 v[14:15], v[34:35], v[14:15]
	s_branch .LBB0_1386
